# comb12 with the K-loop heads placed 2 s_nop past the 64-byte boundary (placement variant)
# speedup vs baseline: 1.0052x; 1.0052x over previous
;     __device__ bool next(int i, Unit& u) const { int pm, pn; if (!so.next(i, pm, pn)) return false; u.pm = pm; u.pn = pn; u.aoff = (unsigned)pm * BM * lda; u.boff = (unsigned)pn * BM * ldb; return true; }
;     __device__ __forceinline__ bool next(int i, Unit& u) const { int pm, pn; if (!so.next(i, pm, pn)) return false; u.pm = pm; u.pn = pn; u.aoff = (unsigned)pm * BM * lda; u.boff = (unsigned)(pm >> 4) * bstride + (unsigned)pn * BM * ldb; return true; }
;     __device__ __forceinline__ bool next(int i, Unit& u) const { int pm, pn; if (!so.next(i, pm, pn)) return false; u.pm = pm; u.pn = ((pn & 12) == 4 || (pn & 12) == 8) ? (pn ^ 12) : pn; u.aoff = (unsigned)pm * BM * lda; u.boff = (unsigned)pn * BM * ldb; return true; }
; template <class Epi, class Sched, bool ALIGN_EPI>
; __device__ __forceinline__ void gemm_phase(LAS unsigned char* lds, const Gemm g, const Sched& S, const Epi& E) {
;     ...
;         const bool has_next = S.next(ui + 1, nxt);
;         const char* nA = has_next ? (const char*)g.A + (size_t)nxt.aoff * 2 : cA; const char* nB = has_next ? (const char*)g.Bt + (size_t)nxt.boff * 2 : cB;
;     ...
; #pragma unroll
;         for (int a = 0; a < 2; ++a)
; #pragma unroll
;             for (int b = 0; b < 2; ++b)
; #pragma unroll
;                 for (int m = 0; m < 4; ++m)
; #pragma unroll
;                     for (int n = 0; n < 2; ++n) acc[a][b][m][n] = (f32x4){0.f, 0.f, 0.f, 0.f};
.LBB0_241:
	s_lshl_b64 s[42:43], s[4:5], 1
	s_add_u32 s42, s79, s42
	s_addc_u32 s43, s80, s43
	s_and_b64 s[44:45], s[38:39], exec
	s_mov_b32 s41, s5
	s_cselect_b32 vcc_lo, s43, s67
	s_cselect_b32 vcc_hi, s42, s66
	s_lshl_b64 s[44:45], s[40:41], 1
	s_add_u32 s64, s62, s44
	s_addc_u32 s65, s63, s45
	s_and_b64 s[44:45], s[38:39], exec
	s_cselect_b32 s41, s65, s69
	s_cselect_b32 s87, s64, s68
	s_add_u32 s66, s66, 0x80080
	s_addc_u32 s67, s67, 0
	s_add_u32 s44, s68, 0x100
	v_mov_b32_e32 v0, 0
	s_addc_u32 s45, s69, 0
	s_mov_b32 s72, -2
	v_mov_b32_e32 v1, v0
	v_mov_b32_e32 v2, v0
	v_mov_b32_e32 v3, v0
	v_mov_b32_e32 v4, v0
	v_mov_b32_e32 v5, v0
	v_mov_b32_e32 v6, v0
	v_mov_b32_e32 v7, v0
	v_mov_b32_e32 v8, v0
	v_mov_b32_e32 v9, v0
	v_mov_b32_e32 v10, v0
	v_mov_b32_e32 v11, v0
	v_mov_b32_e32 v16, v0
	v_mov_b32_e32 v17, v0
	v_mov_b32_e32 v18, v0
	v_mov_b32_e32 v19, v0
	v_mov_b32_e32 v24, v0
	v_mov_b32_e32 v25, v0
	v_mov_b32_e32 v26, v0
	v_mov_b32_e32 v27, v0
	v_mov_b32_e32 v32, v0
	v_mov_b32_e32 v33, v0
	v_mov_b32_e32 v34, v0
	v_mov_b32_e32 v35, v0
	v_mov_b32_e32 v40, v0
	v_mov_b32_e32 v41, v0
	v_mov_b32_e32 v42, v0
	v_mov_b32_e32 v43, v0
	v_mov_b32_e32 v48, v0
	v_mov_b32_e32 v49, v0
	v_mov_b32_e32 v50, v0
	v_mov_b32_e32 v51, v0
	v_mov_b32_e32 v12, v0
	v_mov_b32_e32 v13, v0
	v_mov_b32_e32 v14, v0
	v_mov_b32_e32 v15, v0
	v_mov_b32_e32 v20, v0
	v_mov_b32_e32 v21, v0
	v_mov_b32_e32 v22, v0
	v_mov_b32_e32 v23, v0
	v_mov_b32_e32 v28, v0
	v_mov_b32_e32 v29, v0
	v_mov_b32_e32 v30, v0
	v_mov_b32_e32 v31, v0
	v_mov_b32_e32 v36, v0
	v_mov_b32_e32 v37, v0
	v_mov_b32_e32 v38, v0
	v_mov_b32_e32 v39, v0
	v_mov_b32_e32 v44, v0
	v_mov_b32_e32 v45, v0
	v_mov_b32_e32 v46, v0
	v_mov_b32_e32 v47, v0
	v_mov_b32_e32 v52, v0
	v_mov_b32_e32 v53, v0
	v_mov_b32_e32 v54, v0
	v_mov_b32_e32 v55, v0
	v_mov_b32_e32 v56, v0
	v_mov_b32_e32 v57, v0
	v_mov_b32_e32 v58, v0
	v_mov_b32_e32 v59, v0
	v_mov_b32_e32 v60, v0
	v_mov_b32_e32 v61, v0
	v_mov_b32_e32 v62, v0
	v_mov_b32_e32 v63, v0
	v_mov_b32_e32 v64, v0
	v_mov_b32_e32 v65, v0
	v_mov_b32_e32 v66, v0
	v_mov_b32_e32 v67, v0
	v_mov_b32_e32 v68, v0
	v_mov_b32_e32 v69, v0
	v_mov_b32_e32 v70, v0
	v_mov_b32_e32 v71, v0
	v_mov_b32_e32 v76, v0
	v_mov_b32_e32 v77, v0
	v_mov_b32_e32 v78, v0
	v_mov_b32_e32 v79, v0
	v_mov_b32_e32 v84, v0
	v_mov_b32_e32 v85, v0
	v_mov_b32_e32 v86, v0
	v_mov_b32_e32 v87, v0
	v_mov_b32_e32 v92, v0
	v_mov_b32_e32 v93, v0
	v_mov_b32_e32 v94, v0
	v_mov_b32_e32 v95, v0
	v_mov_b32_e32 v100, v0
	v_mov_b32_e32 v101, v0
	s_waitcnt lgkmcnt(0)
	v_mov_b32_e32 v102, v0
	v_mov_b32_e32 v103, v0
	v_mov_b32_e32 v108, v0
	v_mov_b32_e32 v109, v0
	v_mov_b32_e32 v110, v0
	v_mov_b32_e32 v111, v0
	v_mov_b32_e32 v116, v0
	v_mov_b32_e32 v117, v0
	v_mov_b32_e32 v118, v0
	v_mov_b32_e32 v119, v0
	v_mov_b32_e32 v72, v0
	v_mov_b32_e32 v73, v0
	v_mov_b32_e32 v74, v0
	v_mov_b32_e32 v75, v0
	v_mov_b32_e32 v80, v0
	v_mov_b32_e32 v81, v0
	v_mov_b32_e32 v82, v0
	v_mov_b32_e32 v83, v0
	v_mov_b32_e32 v88, v0
	v_mov_b32_e32 v89, v0
	v_mov_b32_e32 v90, v0
	v_mov_b32_e32 v91, v0
	v_mov_b32_e32 v96, v0
	v_mov_b32_e32 v97, v0
	v_mov_b32_e32 v98, v0
	v_mov_b32_e32 v99, v0
	v_mov_b32_e32 v104, v0
	v_mov_b32_e32 v105, v0
	v_mov_b32_e32 v106, v0
	v_mov_b32_e32 v107, v0
	v_mov_b32_e32 v112, v0
	v_mov_b32_e32 v113, v0
	v_mov_b32_e32 v114, v0
	v_mov_b32_e32 v115, v0
	v_mov_b32_e32 v120, v0
	v_mov_b32_e32 v121, v0
	v_mov_b32_e32 v122, v0
	v_mov_b32_e32 v123, v0
	v_mov_b32_e32 v124, v0
	v_mov_b32_e32 v125, v0
	v_mov_b32_e32 v126, v0
	v_mov_b32_e32 v127, v0
	.p2align 6
	s_nop 0
	s_nop 0

;     __device__ bool next(int i, Unit& u) const { int pm, pn; if (!so.next(i, pm, pn)) return false; u.pm = pm; u.pn = pn; u.aoff = (unsigned)pm * BM * lda; u.boff = (unsigned)pn * BM * ldb; return true; }
;     __device__ __forceinline__ bool next(int i, Unit& u) const { int pm, pn; if (!so.next(i, pm, pn)) return false; u.pm = pm; u.pn = pn; u.aoff = (unsigned)pm * BM * lda; u.boff = (unsigned)(pm >> 4) * bstride + (unsigned)pn * BM * ldb; return true; }
;     __device__ __forceinline__ bool next(int i, Unit& u) const { int pm, pn; if (!so.next(i, pm, pn)) return false; u.pm = pm; u.pn = ((pn & 12) == 4 || (pn & 12) == 8) ? (pn ^ 12) : pn; u.aoff = (unsigned)pm * BM * lda; u.boff = (unsigned)pn * BM * ldb; return true; }
; template <class Epi, class Sched, bool ALIGN_EPI>
; __device__ __forceinline__ void gemm_phase(LAS unsigned char* lds, const Gemm g, const Sched& S, const Epi& E) {
;     ...
;         const bool has_next = S.next(ui + 1, nxt);
;         const char* nA = has_next ? (const char*)g.A + (size_t)nxt.aoff * 2 : cA; const char* nB = has_next ? (const char*)g.Bt + (size_t)nxt.boff * 2 : cB;
;     ...
; #pragma unroll
;         for (int a = 0; a < 2; ++a)
; #pragma unroll
;             for (int b = 0; b < 2; ++b)
; #pragma unroll
;                 for (int m = 0; m < 4; ++m)
; #pragma unroll
;                     for (int n = 0; n < 2; ++n) acc[a][b][m][n] = (f32x4){0.f, 0.f, 0.f, 0.f};
.LBB0_260:
	s_lshl_b64 s[44:45], s[24:25], 1
	s_add_u32 s62, s50, s44
	s_addc_u32 s63, s51, s45
	s_and_b64 s[44:45], s[2:3], exec
	s_mov_b32 s43, s25
	s_cselect_b32 s93, s63, s5
	s_cselect_b32 s94, s62, s4
	s_lshl_b64 s[44:45], s[42:43], 1
	s_add_u32 s64, s14, s44
	s_addc_u32 s65, s15, s45
	s_and_b64 s[44:45], s[2:3], exec
	s_cselect_b32 s43, s65, s7
	s_cselect_b32 s87, s64, s6
	s_add_u32 s4, s4, 0x80080
	s_addc_u32 s5, s5, 0
	s_add_u32 s44, s6, 0x100
	v_mov_b32_e32 v0, 0
	s_addc_u32 s45, s7, 0
	s_mov_b32 s72, -2
	v_mov_b32_e32 v1, v0
	v_mov_b32_e32 v2, v0
	v_mov_b32_e32 v3, v0
	v_mov_b32_e32 v8, v0
	v_mov_b32_e32 v9, v0
	v_mov_b32_e32 v10, v0
	v_mov_b32_e32 v11, v0
	v_mov_b32_e32 v16, v0
	v_mov_b32_e32 v17, v0
	v_mov_b32_e32 v18, v0
	v_mov_b32_e32 v19, v0
	v_mov_b32_e32 v24, v0
	v_mov_b32_e32 v25, v0
	v_mov_b32_e32 v26, v0
	v_mov_b32_e32 v27, v0
	v_mov_b32_e32 v32, v0
	v_mov_b32_e32 v33, v0
	v_mov_b32_e32 v34, v0
	v_mov_b32_e32 v35, v0
	v_mov_b32_e32 v40, v0
	v_mov_b32_e32 v41, v0
	v_mov_b32_e32 v42, v0
	v_mov_b32_e32 v43, v0
	v_mov_b32_e32 v48, v0
	v_mov_b32_e32 v49, v0
	v_mov_b32_e32 v50, v0
	v_mov_b32_e32 v51, v0
	v_mov_b32_e32 v56, v0
	v_mov_b32_e32 v57, v0
	v_mov_b32_e32 v58, v0
	v_mov_b32_e32 v59, v0
	v_mov_b32_e32 v4, v0
	v_mov_b32_e32 v5, v0
	v_mov_b32_e32 v6, v0
	v_mov_b32_e32 v7, v0
	v_mov_b32_e32 v12, v0
	v_mov_b32_e32 v13, v0
	v_mov_b32_e32 v14, v0
	v_mov_b32_e32 v15, v0
	v_mov_b32_e32 v20, v0
	v_mov_b32_e32 v21, v0
	v_mov_b32_e32 v22, v0
	v_mov_b32_e32 v23, v0
	v_mov_b32_e32 v28, v0
	v_mov_b32_e32 v29, v0
	v_mov_b32_e32 v30, v0
	v_mov_b32_e32 v31, v0
	v_mov_b32_e32 v36, v0
	v_mov_b32_e32 v37, v0
	v_mov_b32_e32 v38, v0
	v_mov_b32_e32 v39, v0
	v_mov_b32_e32 v44, v0
	v_mov_b32_e32 v45, v0
	v_mov_b32_e32 v46, v0
	v_mov_b32_e32 v47, v0
	v_mov_b32_e32 v52, v0
	v_mov_b32_e32 v53, v0
	v_mov_b32_e32 v54, v0
	v_mov_b32_e32 v55, v0
	v_mov_b32_e32 v60, v0
	v_mov_b32_e32 v61, v0
	v_mov_b32_e32 v62, v0
	v_mov_b32_e32 v63, v0
	v_mov_b32_e32 v64, v0
	v_mov_b32_e32 v65, v0
	v_mov_b32_e32 v66, v0
	v_mov_b32_e32 v67, v0
	v_mov_b32_e32 v72, v0
	v_mov_b32_e32 v73, v0
	v_mov_b32_e32 v74, v0
	v_mov_b32_e32 v75, v0
	v_mov_b32_e32 v80, v0
	v_mov_b32_e32 v81, v0
	v_mov_b32_e32 v82, v0
	v_mov_b32_e32 v83, v0
	v_mov_b32_e32 v88, v0
	v_mov_b32_e32 v89, v0
	v_mov_b32_e32 v90, v0
	v_mov_b32_e32 v91, v0
	v_mov_b32_e32 v96, v0
	s_waitcnt lgkmcnt(0)
	v_mov_b32_e32 v97, v0
	v_mov_b32_e32 v98, v0
	v_mov_b32_e32 v99, v0
	v_mov_b32_e32 v104, v0
	v_mov_b32_e32 v105, v0
	v_mov_b32_e32 v106, v0
	v_mov_b32_e32 v107, v0
	v_mov_b32_e32 v112, v0
	v_mov_b32_e32 v113, v0
	v_mov_b32_e32 v114, v0
	v_mov_b32_e32 v115, v0
	v_mov_b32_e32 v120, v0
	v_mov_b32_e32 v121, v0
	v_mov_b32_e32 v122, v0
	v_mov_b32_e32 v123, v0
	v_mov_b32_e32 v68, v0
	v_mov_b32_e32 v69, v0
	v_mov_b32_e32 v70, v0
	v_mov_b32_e32 v71, v0
	v_mov_b32_e32 v76, v0
	v_mov_b32_e32 v77, v0
	v_mov_b32_e32 v78, v0
	v_mov_b32_e32 v79, v0
	v_mov_b32_e32 v84, v0
	v_mov_b32_e32 v85, v0
	v_mov_b32_e32 v86, v0
	v_mov_b32_e32 v87, v0
	v_mov_b32_e32 v92, v0
	v_mov_b32_e32 v93, v0
	v_mov_b32_e32 v94, v0
	v_mov_b32_e32 v95, v0
	v_mov_b32_e32 v100, v0
	v_mov_b32_e32 v101, v0
	v_mov_b32_e32 v102, v0
	v_mov_b32_e32 v103, v0
	v_mov_b32_e32 v108, v0
	v_mov_b32_e32 v109, v0
	v_mov_b32_e32 v110, v0
	v_mov_b32_e32 v111, v0
	v_mov_b32_e32 v116, v0
	v_mov_b32_e32 v117, v0
	v_mov_b32_e32 v118, v0
	v_mov_b32_e32 v119, v0
	v_mov_b32_e32 v124, v0
	v_mov_b32_e32 v125, v0
	v_mov_b32_e32 v126, v0
	v_mov_b32_e32 v127, v0
	.p2align 6
	s_nop 0
	s_nop 0

; #define PG8_STAGE(bufoff, gbase, voff) do { _Pragma("unroll") for (int _i = 0; _i < 2; ++_i) \
;         __builtin_amdgcn_global_load_lds((const unsigned*)((const char*)(gbase) + (voff)[_i]), (LAS unsigned*)(lds + (bufoff) + ldsw + _i * 8192), 16, 0, 0); } while (0)
; #define PG8_WAIT_V(n) asm volatile("s_waitcnt vmcnt(" #n ")" ::: "memory")
; #define PG8_BAR __builtin_amdgcn_s_barrier()
; template <class Epi, class Sched, bool ALIGN_EPI>
; __device__ __forceinline__ void gemm_phase(LAS unsigned char* lds, const Gemm g, const Sched& S, const Epi& E) {
;     ...
;     f32x4 acc[2][2][4][2];
; #pragma unroll
;     for (int a = 0; a < 2; ++a)
; #pragma unroll
;         for (int b = 0; b < 2; ++b)
; #pragma unroll
;             for (int m = 0; m < 4; ++m)
; #pragma unroll
;                 for (int n = 0; n < 2; ++n) acc[a][b][m][n] = (f32x4){0.f, 0.f, 0.f, 0.f};
;     ...
;     PG8_STAGE(PG8_SB(0, 0), cB, voffB); PG8_STAGE(PG8_SB(0, 1), cB + hB, voffB); PG8_STAGE(PG8_SA(0, 0), cA, voffA); PG8_STAGE(PG8_SA(0, 1), cA + hA, voffA);
;     if (wr == 1) PG8_BAR;
;     PG8_WAIT_V(2); PG8_BAR;
;     PG8_STAGE(PG8_SB(1, 0), cB + kstep, voffB); PG8_STAGE(PG8_SA(1, 0), cA + kstep, voffA); PG8_STAGE(PG8_SB(1, 1), cB + hB + kstep, voffB);
;     PG8_WAIT_V(6); PG8_BAR;
.LBB0_278:
	s_lshl_b32 s6, s42, 5
	s_add_i32 m0, s27, 0x18000
	v_lshl_add_u64 v[0:1], v[0:1], 0, s[24:25]
	s_and_b32 s74, s6, 0x60
	s_waitcnt vmcnt(2)
	s_barrier
	global_load_lds_dwordx4 v[0:1], off
	v_lshl_add_u64 v[0:1], v[2:3], 0, s[24:25]
	s_add_i32 m0, s27, 0x1a000
	s_add_i32 s78, s27, 0x8000
	s_add_i32 s79, s27, 0xa000
	global_load_lds_dwordx4 v[0:1], off
	v_lshl_add_u64 v[0:1], v[6:7], 0, s[24:25]
	s_mov_b32 m0, s78
	s_add_u32 s42, s36, 0x80080
	global_load_lds_dwordx4 v[0:1], off
	v_lshl_add_u64 v[0:1], v[4:5], 0, s[24:25]
	s_mov_b32 m0, s79
	s_addc_u32 s43, s37, 0
	global_load_lds_dwordx4 v[0:1], off
	s_add_i32 m0, s27, 0x1c000
	v_lshl_add_u64 v[0:1], s[42:43], 0, v[144:145]
	global_load_lds_dwordx4 v[0:1], off
	v_lshl_add_u64 v[0:1], s[42:43], 0, v[146:147]
	s_add_i32 m0, s27, 0x1e000
	v_mov_b32_e32 v127, 0
	global_load_lds_dwordx4 v[0:1], off
	s_waitcnt vmcnt(6)
	v_lshl_or_b32 v132, s41, 6, v182
	s_and_b64 vcc, exec, s[4:5]
	v_mov_b32_e32 v126, v127
	v_mov_b32_e32 v125, v127
	v_mov_b32_e32 v124, v127
	v_mov_b32_e32 v123, v127
	v_mov_b32_e32 v122, v127
	v_mov_b32_e32 v121, v127
	v_mov_b32_e32 v120, v127
	v_mov_b32_e32 v111, v127
	v_mov_b32_e32 v110, v127
	v_mov_b32_e32 v109, v127
	v_mov_b32_e32 v108, v127
	v_mov_b32_e32 v107, v127
	v_mov_b32_e32 v106, v127
	v_mov_b32_e32 v105, v127
	v_mov_b32_e32 v104, v127
	v_mov_b32_e32 v95, v127
	v_mov_b32_e32 v94, v127
	v_mov_b32_e32 v93, v127
	v_mov_b32_e32 v92, v127
	v_mov_b32_e32 v91, v127
	v_mov_b32_e32 v90, v127
	v_mov_b32_e32 v89, v127
	v_mov_b32_e32 v88, v127
	v_mov_b32_e32 v79, v127
	v_mov_b32_e32 v78, v127
	v_mov_b32_e32 v77, v127
	v_mov_b32_e32 v76, v127
	v_mov_b32_e32 v75, v127
	v_mov_b32_e32 v74, v127
	v_mov_b32_e32 v73, v127
	v_mov_b32_e32 v72, v127
	v_mov_b32_e32 v119, v127
	v_mov_b32_e32 v118, v127
	v_mov_b32_e32 v117, v127
	v_mov_b32_e32 v116, v127
	v_mov_b32_e32 v115, v127
	v_mov_b32_e32 v114, v127
	v_mov_b32_e32 v113, v127
	v_mov_b32_e32 v112, v127
	v_mov_b32_e32 v103, v127
	v_mov_b32_e32 v102, v127
	v_mov_b32_e32 v101, v127
	v_mov_b32_e32 v100, v127
	v_mov_b32_e32 v99, v127
	v_mov_b32_e32 v98, v127
	v_mov_b32_e32 v97, v127
	v_mov_b32_e32 v96, v127
	v_mov_b32_e32 v87, v127
	v_mov_b32_e32 v86, v127
	v_mov_b32_e32 v85, v127
	v_mov_b32_e32 v84, v127
	v_mov_b32_e32 v83, v127
	v_mov_b32_e32 v82, v127
	v_mov_b32_e32 v81, v127
	v_mov_b32_e32 v80, v127
	v_mov_b32_e32 v71, v127
	v_mov_b32_e32 v70, v127
	v_mov_b32_e32 v69, v127
	v_mov_b32_e32 v68, v127
	v_mov_b32_e32 v67, v127
	v_mov_b32_e32 v66, v127
	v_mov_b32_e32 v65, v127
	v_mov_b32_e32 v64, v127
	v_mov_b32_e32 v63, v127
	v_mov_b32_e32 v62, v127
	v_mov_b32_e32 v61, v127
	v_mov_b32_e32 v60, v127
	v_mov_b32_e32 v59, v127
	v_mov_b32_e32 v58, v127
	v_mov_b32_e32 v57, v127
	v_mov_b32_e32 v56, v127
	v_mov_b32_e32 v47, v127
	v_mov_b32_e32 v46, v127
	v_mov_b32_e32 v45, v127
	v_mov_b32_e32 v44, v127
	v_mov_b32_e32 v43, v127
	v_mov_b32_e32 v42, v127
	v_mov_b32_e32 v41, v127
	v_mov_b32_e32 v40, v127
	v_mov_b32_e32 v31, v127
	v_mov_b32_e32 v30, v127
	v_mov_b32_e32 v29, v127
	v_mov_b32_e32 v28, v127
	v_mov_b32_e32 v27, v127
	v_mov_b32_e32 v26, v127
	v_mov_b32_e32 v25, v127
	v_mov_b32_e32 v24, v127
	v_mov_b32_e32 v15, v127
	v_mov_b32_e32 v14, v127
	v_mov_b32_e32 v13, v127
	v_mov_b32_e32 v12, v127
	v_mov_b32_e32 v11, v127
	v_mov_b32_e32 v10, v127
	v_mov_b32_e32 v9, v127
	v_mov_b32_e32 v8, v127
	v_mov_b32_e32 v55, v127
	v_mov_b32_e32 v54, v127
	v_mov_b32_e32 v53, v127
	v_mov_b32_e32 v52, v127
	v_mov_b32_e32 v51, v127
	v_mov_b32_e32 v50, v127
	v_mov_b32_e32 v49, v127
	v_mov_b32_e32 v48, v127
	v_mov_b32_e32 v39, v127
	v_mov_b32_e32 v38, v127
	v_mov_b32_e32 v37, v127
	v_mov_b32_e32 v36, v127
	v_mov_b32_e32 v35, v127
	v_mov_b32_e32 v34, v127
	v_mov_b32_e32 v33, v127
	v_mov_b32_e32 v32, v127
	v_mov_b32_e32 v23, v127
	v_mov_b32_e32 v22, v127
	v_mov_b32_e32 v21, v127
	v_mov_b32_e32 v20, v127
	v_mov_b32_e32 v19, v127
	v_mov_b32_e32 v18, v127
	v_mov_b32_e32 v17, v127
	v_mov_b32_e32 v16, v127
	v_mov_b32_e32 v7, v127
	v_mov_b32_e32 v6, v127
	v_mov_b32_e32 v5, v127
	v_mov_b32_e32 v4, v127
	v_mov_b32_e32 v3, v127
	v_mov_b32_e32 v2, v127
	v_mov_b32_e32 v1, v127
	v_mov_b32_e32 v0, v127
	s_barrier
; template <class Epi, class Sched, bool ALIGN_EPI>
; __device__ __forceinline__ void gemm_phase(LAS unsigned char* lds, const Gemm g, const Sched& S, const Epi& E) {
;     const int tid = threadIdx.x, wid = __builtin_amdgcn_readfirstlane(tid >> 6), lane = tid & 63, wr = wid >> 2, wc = wid & 3, fr = lane & 15, fq = lane >> 4;
;     const int K = g.K, nt = K / BK;
;     unsigned voffA[2], voffB[2];
; #pragma unroll
;     for (int i = 0; i < 2; ++i) { int R, C; stage_rc(tid * 16 + i * 8192, R, C); const int Rb = Epi::PERM ? ((R & ~31) + perm32(R & 31)) : R;
;         voffA[i] = (unsigned)(R * g.lda + C) * 2u; voffB[i] = (unsigned)(Rb * g.ldb + C) * 2u; }
;     const size_t kstep = (size_t)(BK * 2);
;     const size_t hA = (size_t)HALF * g.lda * 2, hB = (size_t)HALF * g.ldb * 2;
;     const unsigned ldsw = (unsigned)wid * 1024u;
;     const int aoff = lds_byte(wr * 64 + fr, fq * 8), boff = lds_byte(wc * 32 + fr, fq * 8);
;     ...
;     f32x4 acc[2][2][4][2];
; #pragma unroll
;     for (int a = 0; a < 2; ++a)
; #pragma unroll
;         for (int b = 0; b < 2; ++b)
; #pragma unroll
;             for (int m = 0; m < 4; ++m)
; #pragma unroll
;                 for (int n = 0; n < 2; ++n) acc[a][b][m][n] = (f32x4){0.f, 0.f, 0.f, 0.f};
	s_cbranch_vccnz .LBB0_281
	s_lshr_b32 s6, s64, 3
	s_and_b32 s6, s6, 3
	v_lshlrev_b32_e32 v0, 6, v132
	v_lshlrev_b32_e32 v1, 2, v132
	s_lshl_b32 s6, s6, 9
	v_and_or_b32 v0, v0, s67, v183
	v_and_b32_e32 v1, 32, v1
	s_lshl_b32 s18, s41, 13
	s_add_i32 s6, s40, s6
	v_lshl_or_b32 v142, s74, 7, v184
	v_bitop3_b32 v1, v0, s18, v1 bitop3:0xde
	s_lshl_b64 s[40:41], s[6:7], 1
	v_mov_b32_e32 v0, 0
	s_add_i32 s45, s68, s11
	s_add_i32 s47, s69, s11
	v_lshl_add_u64 v[138:139], v[134:135], 0, s[40:41]
	v_lshl_add_u64 v[140:141], v[136:137], 0, s[40:41]
	s_mov_b32 s42, 0
	s_mov_b64 s[40:41], 0xc000080
	v_add_u32_e32 v143, 0, v1
	v_add_u32_e32 v148, s68, v142
	v_add_u32_e32 v149, s69, v142
	s_add_i32 s6, s27, 0xc000
	s_add_i32 s44, s27, 0xe000
	s_add_i32 s46, s45, 0x2000
	s_add_i32 s72, s47, 0x2000
	v_mov_b32_e32 v1, v0
	v_mov_b32_e32 v2, v0
	v_mov_b32_e32 v3, v0
	v_mov_b32_e32 v4, v0
	v_mov_b32_e32 v5, v0
	v_mov_b32_e32 v6, v0
	v_mov_b32_e32 v7, v0
	v_mov_b32_e32 v16, v0
	v_mov_b32_e32 v17, v0
	v_mov_b32_e32 v18, v0
	v_mov_b32_e32 v19, v0
	v_mov_b32_e32 v20, v0
	v_mov_b32_e32 v21, v0
	v_mov_b32_e32 v22, v0
	v_mov_b32_e32 v23, v0
	v_mov_b32_e32 v32, v0
	v_mov_b32_e32 v33, v0
	v_mov_b32_e32 v34, v0
	v_mov_b32_e32 v35, v0
	v_mov_b32_e32 v36, v0
	v_mov_b32_e32 v37, v0
	v_mov_b32_e32 v38, v0
	v_mov_b32_e32 v39, v0
	v_mov_b32_e32 v48, v0
	v_mov_b32_e32 v49, v0
	v_mov_b32_e32 v50, v0
	v_mov_b32_e32 v51, v0
	v_mov_b32_e32 v52, v0
	v_mov_b32_e32 v53, v0
	v_mov_b32_e32 v54, v0
	v_mov_b32_e32 v55, v0
	v_mov_b32_e32 v8, v0
	v_mov_b32_e32 v9, v0
	v_mov_b32_e32 v10, v0
	v_mov_b32_e32 v11, v0
	v_mov_b32_e32 v12, v0
	v_mov_b32_e32 v13, v0
	v_mov_b32_e32 v14, v0
	v_mov_b32_e32 v15, v0
	v_mov_b32_e32 v24, v0
	v_mov_b32_e32 v25, v0
	v_mov_b32_e32 v26, v0
	v_mov_b32_e32 v27, v0
	v_mov_b32_e32 v28, v0
	v_mov_b32_e32 v29, v0
	v_mov_b32_e32 v30, v0
	v_mov_b32_e32 v31, v0
	v_mov_b32_e32 v40, v0
	v_mov_b32_e32 v41, v0
	v_mov_b32_e32 v42, v0
	v_mov_b32_e32 v43, v0
	v_mov_b32_e32 v44, v0
	v_mov_b32_e32 v45, v0
	v_mov_b32_e32 v46, v0
	v_mov_b32_e32 v47, v0
	v_mov_b32_e32 v56, v0
	v_mov_b32_e32 v57, v0
	v_mov_b32_e32 v58, v0
	v_mov_b32_e32 v59, v0
	v_mov_b32_e32 v60, v0
	v_mov_b32_e32 v61, v0
	v_mov_b32_e32 v62, v0
	v_mov_b32_e32 v63, v0
	v_mov_b32_e32 v64, v0
	v_mov_b32_e32 v65, v0
	v_mov_b32_e32 v66, v0
	v_mov_b32_e32 v67, v0
	v_mov_b32_e32 v68, v0
	v_mov_b32_e32 v69, v0
	v_mov_b32_e32 v70, v0
	v_mov_b32_e32 v71, v0
	v_mov_b32_e32 v80, v0
	v_mov_b32_e32 v81, v0
	v_mov_b32_e32 v82, v0
	v_mov_b32_e32 v83, v0
	v_mov_b32_e32 v84, v0
	v_mov_b32_e32 v85, v0
	v_mov_b32_e32 v86, v0
	v_mov_b32_e32 v87, v0
	v_mov_b32_e32 v96, v0
	v_mov_b32_e32 v97, v0
	v_mov_b32_e32 v98, v0
	v_mov_b32_e32 v99, v0
	v_mov_b32_e32 v100, v0
	v_mov_b32_e32 v101, v0
	v_mov_b32_e32 v102, v0
	v_mov_b32_e32 v103, v0
	v_mov_b32_e32 v112, v0
	v_mov_b32_e32 v113, v0
	v_mov_b32_e32 v114, v0
	v_mov_b32_e32 v115, v0
	v_mov_b32_e32 v116, v0
	v_mov_b32_e32 v117, v0
	v_mov_b32_e32 v118, v0
	v_mov_b32_e32 v119, v0
	v_mov_b32_e32 v72, v0
	v_mov_b32_e32 v73, v0
	v_mov_b32_e32 v74, v0
	v_mov_b32_e32 v75, v0
	v_mov_b32_e32 v76, v0
	v_mov_b32_e32 v77, v0
	v_mov_b32_e32 v78, v0
	v_mov_b32_e32 v79, v0
	v_mov_b32_e32 v88, v0
	v_mov_b32_e32 v89, v0
	v_mov_b32_e32 v90, v0
	v_mov_b32_e32 v91, v0
	v_mov_b32_e32 v92, v0
	v_mov_b32_e32 v93, v0
	v_mov_b32_e32 v94, v0
	v_mov_b32_e32 v95, v0
	v_mov_b32_e32 v104, v0
	v_mov_b32_e32 v105, v0
	v_mov_b32_e32 v106, v0
	v_mov_b32_e32 v107, v0
	v_mov_b32_e32 v108, v0
	v_mov_b32_e32 v109, v0
	v_mov_b32_e32 v110, v0
	v_mov_b32_e32 v111, v0
	v_mov_b32_e32 v120, v0
	v_mov_b32_e32 v121, v0
	v_mov_b32_e32 v122, v0
	v_mov_b32_e32 v123, v0
	v_mov_b32_e32 v124, v0
	v_mov_b32_e32 v125, v0
	v_mov_b32_e32 v126, v0
	v_mov_b32_e32 v127, v0
	.p2align 6
	s_nop 0
	s_nop 0

;     __device__ bool next(int i, Unit& u) const { int pm, pn; if (!so.next(i, pm, pn)) return false; u.pm = pm; u.pn = pn; u.aoff = (unsigned)pm * BM * lda; u.boff = (unsigned)pn * BM * ldb; return true; }
;     __device__ __forceinline__ bool next(int i, Unit& u) const { int pm, pn; if (!so.next(i, pm, pn)) return false; u.pm = pm; u.pn = pn; u.aoff = (unsigned)pm * BM * lda; u.boff = (unsigned)(pm >> 4) * bstride + (unsigned)pn * BM * ldb; return true; }
;     __device__ __forceinline__ bool next(int i, Unit& u) const { int pm, pn; if (!so.next(i, pm, pn)) return false; u.pm = pm; u.pn = ((pn & 12) == 4 || (pn & 12) == 8) ? (pn ^ 12) : pn; u.aoff = (unsigned)pm * BM * lda; u.boff = (unsigned)pn * BM * ldb; return true; }
; template <class Epi, class Sched, bool ALIGN_EPI>
; __device__ __forceinline__ void gemm_phase(LAS unsigned char* lds, const Gemm g, const Sched& S, const Epi& E) {
;     ...
;         const bool has_next = S.next(ui + 1, nxt);
;         const char* nA = has_next ? (const char*)g.A + (size_t)nxt.aoff * 2 : cA; const char* nB = has_next ? (const char*)g.Bt + (size_t)nxt.boff * 2 : cB;
;     ...
; #pragma unroll
;         for (int a = 0; a < 2; ++a)
; #pragma unroll
;             for (int b = 0; b < 2; ++b)
; #pragma unroll
;                 for (int m = 0; m < 4; ++m)
; #pragma unroll
;                     for (int n = 0; n < 2; ++n) acc[a][b][m][n] = (f32x4){0.f, 0.f, 0.f, 0.f};
.LBB0_360:
	s_lshl_b64 s[38:39], s[20:21], 1
	s_add_u32 s38, s28, s38
	s_addc_u32 s39, s29, s39
	s_and_b64 s[40:41], s[4:5], exec
	s_mov_b32 s37, s21
	s_cselect_b32 s81, s39, s43
	s_cselect_b32 s82, s38, s42
	s_lshl_b64 s[40:41], s[36:37], 1
	s_add_u32 s40, s58, s40
	s_addc_u32 s41, s59, s41
	s_and_b64 s[44:45], s[4:5], exec
	s_cselect_b32 s37, s41, s61
	s_cselect_b32 s83, s40, s60
	s_add_u32 s42, s42, 0x160080
	s_addc_u32 s43, s43, 0
	s_add_u32 s44, s60, 0x100
	v_mov_b32_e32 v0, 0
	s_addc_u32 s45, s61, 0
	s_mov_b32 s84, -2
	s_waitcnt lgkmcnt(0)
	v_mov_b32_e32 v1, v0
	v_mov_b32_e32 v2, v0
	v_mov_b32_e32 v3, v0
	v_mov_b32_e32 v4, v0
	v_mov_b32_e32 v5, v0
	v_mov_b32_e32 v6, v0
	v_mov_b32_e32 v7, v0
	v_mov_b32_e32 v16, v0
	v_mov_b32_e32 v17, v0
	v_mov_b32_e32 v18, v0
	v_mov_b32_e32 v19, v0
	v_mov_b32_e32 v20, v0
	v_mov_b32_e32 v21, v0
	v_mov_b32_e32 v22, v0
	v_mov_b32_e32 v23, v0
	v_mov_b32_e32 v32, v0
	v_mov_b32_e32 v33, v0
	v_mov_b32_e32 v34, v0
	v_mov_b32_e32 v35, v0
	v_mov_b32_e32 v36, v0
	v_mov_b32_e32 v37, v0
	v_mov_b32_e32 v38, v0
	v_mov_b32_e32 v39, v0
	v_mov_b32_e32 v48, v0
	v_mov_b32_e32 v49, v0
	v_mov_b32_e32 v50, v0
	v_mov_b32_e32 v51, v0
	v_mov_b32_e32 v52, v0
	v_mov_b32_e32 v53, v0
	v_mov_b32_e32 v54, v0
	v_mov_b32_e32 v55, v0
	v_mov_b32_e32 v8, v0
	v_mov_b32_e32 v9, v0
	v_mov_b32_e32 v10, v0
	v_mov_b32_e32 v11, v0
	v_mov_b32_e32 v12, v0
	v_mov_b32_e32 v13, v0
	v_mov_b32_e32 v14, v0
	v_mov_b32_e32 v15, v0
	v_mov_b32_e32 v24, v0
	v_mov_b32_e32 v25, v0
	v_mov_b32_e32 v26, v0
	v_mov_b32_e32 v27, v0
	v_mov_b32_e32 v28, v0
	v_mov_b32_e32 v29, v0
	v_mov_b32_e32 v30, v0
	v_mov_b32_e32 v31, v0
	v_mov_b32_e32 v40, v0
	v_mov_b32_e32 v41, v0
	v_mov_b32_e32 v42, v0
	v_mov_b32_e32 v43, v0
	v_mov_b32_e32 v44, v0
	v_mov_b32_e32 v45, v0
	v_mov_b32_e32 v46, v0
	v_mov_b32_e32 v47, v0
	v_mov_b32_e32 v56, v0
	v_mov_b32_e32 v57, v0
	v_mov_b32_e32 v58, v0
	v_mov_b32_e32 v59, v0
	v_mov_b32_e32 v60, v0
	v_mov_b32_e32 v61, v0
	v_mov_b32_e32 v62, v0
	v_mov_b32_e32 v63, v0
	v_mov_b32_e32 v64, v0
	v_mov_b32_e32 v65, v0
	v_mov_b32_e32 v66, v0
	v_mov_b32_e32 v67, v0
	v_mov_b32_e32 v68, v0
	v_mov_b32_e32 v69, v0
	v_mov_b32_e32 v70, v0
	v_mov_b32_e32 v71, v0
	v_mov_b32_e32 v80, v0
	v_mov_b32_e32 v81, v0
	v_mov_b32_e32 v82, v0
	v_mov_b32_e32 v83, v0
	v_mov_b32_e32 v84, v0
	v_mov_b32_e32 v85, v0
	v_mov_b32_e32 v86, v0
	v_mov_b32_e32 v87, v0
	v_mov_b32_e32 v96, v0
	s_waitcnt lgkmcnt(0)
	v_mov_b32_e32 v97, v0
	v_mov_b32_e32 v98, v0
	v_mov_b32_e32 v99, v0
	v_mov_b32_e32 v100, v0
	v_mov_b32_e32 v101, v0
	v_mov_b32_e32 v102, v0
	v_mov_b32_e32 v103, v0
	v_mov_b32_e32 v112, v0
	v_mov_b32_e32 v113, v0
	v_mov_b32_e32 v114, v0
	v_mov_b32_e32 v115, v0
	v_mov_b32_e32 v116, v0
	v_mov_b32_e32 v117, v0
	v_mov_b32_e32 v118, v0
	v_mov_b32_e32 v119, v0
	v_mov_b32_e32 v72, v0
	v_mov_b32_e32 v73, v0
	v_mov_b32_e32 v74, v0
	v_mov_b32_e32 v75, v0
	v_mov_b32_e32 v76, v0
	v_mov_b32_e32 v77, v0
	v_mov_b32_e32 v78, v0
	v_mov_b32_e32 v79, v0
	v_mov_b32_e32 v88, v0
	v_mov_b32_e32 v89, v0
	v_mov_b32_e32 v90, v0
	v_mov_b32_e32 v91, v0
	v_mov_b32_e32 v92, v0
	v_mov_b32_e32 v93, v0
	v_mov_b32_e32 v94, v0
	v_mov_b32_e32 v95, v0
	v_mov_b32_e32 v104, v0
	v_mov_b32_e32 v105, v0
	v_mov_b32_e32 v106, v0
	v_mov_b32_e32 v107, v0
	v_mov_b32_e32 v108, v0
	v_mov_b32_e32 v109, v0
	v_mov_b32_e32 v110, v0
	v_mov_b32_e32 v111, v0
	v_mov_b32_e32 v120, v0
	v_mov_b32_e32 v121, v0
	v_mov_b32_e32 v122, v0
	v_mov_b32_e32 v123, v0
	v_mov_b32_e32 v124, v0
	v_mov_b32_e32 v125, v0
	v_mov_b32_e32 v126, v0
	v_mov_b32_e32 v127, v0
	.p2align 6
	s_nop 0
	s_nop 0

;     __device__ bool next(int i, Unit& u) const { int pm, pn; if (!so.next(i, pm, pn)) return false; u.pm = pm; u.pn = pn; u.aoff = (unsigned)pm * BM * lda; u.boff = (unsigned)pn * BM * ldb; return true; }
;     __device__ __forceinline__ bool next(int i, Unit& u) const { int pm, pn; if (!so.next(i, pm, pn)) return false; u.pm = pm; u.pn = pn; u.aoff = (unsigned)pm * BM * lda; u.boff = (unsigned)(pm >> 4) * bstride + (unsigned)pn * BM * ldb; return true; }
;     __device__ __forceinline__ bool next(int i, Unit& u) const { int pm, pn; if (!so.next(i, pm, pn)) return false; u.pm = pm; u.pn = ((pn & 12) == 4 || (pn & 12) == 8) ? (pn ^ 12) : pn; u.aoff = (unsigned)pm * BM * lda; u.boff = (unsigned)pn * BM * ldb; return true; }
; template <class Epi, class Sched, bool ALIGN_EPI>
; __device__ __forceinline__ void gemm_phase(LAS unsigned char* lds, const Gemm g, const Sched& S, const Epi& E) {
;     ...
;         const bool has_next = S.next(ui + 1, nxt);
;         const char* nA = has_next ? (const char*)g.A + (size_t)nxt.aoff * 2 : cA; const char* nB = has_next ? (const char*)g.Bt + (size_t)nxt.boff * 2 : cB;
;     ...
; #pragma unroll
;         for (int a = 0; a < 2; ++a)
; #pragma unroll
;             for (int b = 0; b < 2; ++b)
; #pragma unroll
;                 for (int m = 0; m < 4; ++m)
; #pragma unroll
;                     for (int n = 0; n < 2; ++n) acc[a][b][m][n] = (f32x4){0.f, 0.f, 0.f, 0.f};
.LBB0_465:
	s_lshl_b64 s[44:45], s[22:23], 1
	s_add_u32 s76, s50, s44
	s_addc_u32 s77, s51, s45
	s_and_b64 s[44:45], s[4:5], exec
	s_mov_b32 s75, s23
	s_cselect_b32 vcc_lo, s77, s7
	s_cselect_b32 vcc_hi, s76, s6
	s_lshl_b64 s[44:45], s[74:75], 1
	s_add_u32 s78, s56, s44
	s_addc_u32 s79, s57, s45
	s_and_b64 s[44:45], s[4:5], exec
	s_cselect_b32 s75, s79, s81
	s_cselect_b32 s87, s78, s80
	s_add_u32 s6, s6, 0x80080
	s_addc_u32 s7, s7, 0
	s_add_u32 s44, s80, 0x100
	v_mov_b32_e32 v0, 0
	s_addc_u32 s45, s81, 0
	s_mov_b32 s46, -2
	v_mov_b32_e32 v1, v0
	v_mov_b32_e32 v2, v0
	v_mov_b32_e32 v3, v0
	v_mov_b32_e32 v8, v0
	v_mov_b32_e32 v9, v0
	v_mov_b32_e32 v10, v0
	v_mov_b32_e32 v11, v0
	v_mov_b32_e32 v16, v0
	v_mov_b32_e32 v17, v0
	v_mov_b32_e32 v18, v0
	v_mov_b32_e32 v19, v0
	v_mov_b32_e32 v24, v0
	v_mov_b32_e32 v25, v0
	v_mov_b32_e32 v26, v0
	v_mov_b32_e32 v27, v0
	v_mov_b32_e32 v32, v0
	v_mov_b32_e32 v33, v0
	v_mov_b32_e32 v34, v0
	v_mov_b32_e32 v35, v0
	v_mov_b32_e32 v40, v0
	v_mov_b32_e32 v41, v0
	v_mov_b32_e32 v42, v0
	v_mov_b32_e32 v43, v0
	v_mov_b32_e32 v48, v0
	v_mov_b32_e32 v49, v0
	v_mov_b32_e32 v50, v0
	v_mov_b32_e32 v51, v0
	v_mov_b32_e32 v56, v0
	v_mov_b32_e32 v57, v0
	v_mov_b32_e32 v58, v0
	v_mov_b32_e32 v59, v0
	v_mov_b32_e32 v4, v0
	v_mov_b32_e32 v5, v0
	v_mov_b32_e32 v6, v0
	v_mov_b32_e32 v7, v0
	v_mov_b32_e32 v12, v0
	v_mov_b32_e32 v13, v0
	v_mov_b32_e32 v14, v0
	v_mov_b32_e32 v15, v0
	v_mov_b32_e32 v20, v0
	v_mov_b32_e32 v21, v0
	v_mov_b32_e32 v22, v0
	v_mov_b32_e32 v23, v0
	v_mov_b32_e32 v28, v0
	v_mov_b32_e32 v29, v0
	v_mov_b32_e32 v30, v0
	v_mov_b32_e32 v31, v0
	v_mov_b32_e32 v36, v0
	v_mov_b32_e32 v37, v0
	v_mov_b32_e32 v38, v0
	v_mov_b32_e32 v39, v0
	v_mov_b32_e32 v44, v0
	v_mov_b32_e32 v45, v0
	v_mov_b32_e32 v46, v0
	v_mov_b32_e32 v47, v0
	v_mov_b32_e32 v52, v0
	v_mov_b32_e32 v53, v0
	v_mov_b32_e32 v54, v0
	v_mov_b32_e32 v55, v0
	v_mov_b32_e32 v60, v0
	v_mov_b32_e32 v61, v0
	v_mov_b32_e32 v62, v0
	v_mov_b32_e32 v63, v0
	v_mov_b32_e32 v64, v0
	v_mov_b32_e32 v65, v0
	v_mov_b32_e32 v66, v0
	v_mov_b32_e32 v67, v0
	v_mov_b32_e32 v72, v0
	v_mov_b32_e32 v73, v0
	v_mov_b32_e32 v74, v0
	v_mov_b32_e32 v75, v0
	v_mov_b32_e32 v80, v0
	v_mov_b32_e32 v81, v0
	v_mov_b32_e32 v82, v0
	v_mov_b32_e32 v83, v0
	v_mov_b32_e32 v88, v0
	v_mov_b32_e32 v89, v0
	v_mov_b32_e32 v90, v0
	v_mov_b32_e32 v91, v0
	v_mov_b32_e32 v96, v0
	v_mov_b32_e32 v97, v0
	v_mov_b32_e32 v98, v0
	v_mov_b32_e32 v99, v0
	v_mov_b32_e32 v104, v0
	v_mov_b32_e32 v105, v0
	v_mov_b32_e32 v106, v0
	v_mov_b32_e32 v107, v0
	v_mov_b32_e32 v112, v0
	v_mov_b32_e32 v113, v0
	v_mov_b32_e32 v114, v0
	v_mov_b32_e32 v115, v0
	v_mov_b32_e32 v120, v0
	v_mov_b32_e32 v121, v0
	v_mov_b32_e32 v122, v0
	v_mov_b32_e32 v123, v0
	v_mov_b32_e32 v68, v0
	v_mov_b32_e32 v69, v0
	v_mov_b32_e32 v70, v0
	v_mov_b32_e32 v71, v0
	v_mov_b32_e32 v76, v0
	v_mov_b32_e32 v77, v0
	v_mov_b32_e32 v78, v0
	v_mov_b32_e32 v79, v0
	v_mov_b32_e32 v84, v0
	v_mov_b32_e32 v85, v0
	v_mov_b32_e32 v86, v0
	v_mov_b32_e32 v87, v0
	v_mov_b32_e32 v92, v0
	v_mov_b32_e32 v93, v0
	v_mov_b32_e32 v94, v0
	v_mov_b32_e32 v95, v0
	v_mov_b32_e32 v100, v0
	v_mov_b32_e32 v101, v0
	v_mov_b32_e32 v102, v0
	v_mov_b32_e32 v103, v0
	v_mov_b32_e32 v108, v0
	v_mov_b32_e32 v109, v0
	v_mov_b32_e32 v110, v0
	v_mov_b32_e32 v111, v0
	v_mov_b32_e32 v116, v0
	v_mov_b32_e32 v117, v0
	v_mov_b32_e32 v118, v0
	v_mov_b32_e32 v119, v0
	v_mov_b32_e32 v124, v0
	v_mov_b32_e32 v125, v0
	v_mov_b32_e32 v126, v0
	v_mov_b32_e32 v127, v0
	.p2align 6
	s_nop 0
	s_nop 0

;     __device__ bool next(int i, Unit& u) const { int pm, pn; if (!so.next(i, pm, pn)) return false; u.pm = pm; u.pn = pn; u.aoff = (unsigned)pm * BM * lda; u.boff = (unsigned)pn * BM * ldb; return true; }
;     __device__ __forceinline__ bool next(int i, Unit& u) const { int pm, pn; if (!so.next(i, pm, pn)) return false; u.pm = pm; u.pn = pn; u.aoff = (unsigned)pm * BM * lda; u.boff = (unsigned)(pm >> 4) * bstride + (unsigned)pn * BM * ldb; return true; }
;     __device__ __forceinline__ bool next(int i, Unit& u) const { int pm, pn; if (!so.next(i, pm, pn)) return false; u.pm = pm; u.pn = ((pn & 12) == 4 || (pn & 12) == 8) ? (pn ^ 12) : pn; u.aoff = (unsigned)pm * BM * lda; u.boff = (unsigned)pn * BM * ldb; return true; }
; template <class Epi, class Sched, bool ALIGN_EPI>
; __device__ __forceinline__ void gemm_phase(LAS unsigned char* lds, const Gemm g, const Sched& S, const Epi& E) {
;     ...
;         const bool has_next = S.next(ui + 1, nxt);
;         const char* nA = has_next ? (const char*)g.A + (size_t)nxt.aoff * 2 : cA; const char* nB = has_next ? (const char*)g.Bt + (size_t)nxt.boff * 2 : cB;
;     ...
; #pragma unroll
;         for (int a = 0; a < 2; ++a)
; #pragma unroll
;             for (int b = 0; b < 2; ++b)
; #pragma unroll
;                 for (int m = 0; m < 4; ++m)
; #pragma unroll
;                     for (int n = 0; n < 2; ++n) acc[a][b][m][n] = (f32x4){0.f, 0.f, 0.f, 0.f};
.LBB0_844:
	s_lshl_b64 s[18:19], s[22:23], 1
	s_add_u32 s42, s6, s18
	s_addc_u32 s43, s7, s19
	s_and_b64 s[18:19], s[4:5], exec
	s_mov_b32 s41, s23
	s_cselect_b32 s81, s43, s59
	s_cselect_b32 s82, s42, s58
	s_lshl_b64 s[18:19], s[40:41], 1
	s_add_u32 s56, s54, s18
	s_addc_u32 s57, s55, s19
	s_and_b64 s[18:19], s[4:5], exec
	s_cselect_b32 s41, s57, s61
	s_cselect_b32 s83, s56, s60
	s_add_u32 s58, s58, 0x80080
	s_addc_u32 s59, s59, 0
	s_add_u32 s44, s60, 0x100
	v_mov_b32_e32 v0, 0
	s_addc_u32 s45, s61, 0
	s_mov_b32 s46, -2
	s_waitcnt lgkmcnt(0)
	v_mov_b32_e32 v1, v0
	v_mov_b32_e32 v2, v0
	v_mov_b32_e32 v3, v0
	v_mov_b32_e32 v4, v0
	v_mov_b32_e32 v5, v0
	v_mov_b32_e32 v6, v0
	v_mov_b32_e32 v7, v0
	v_mov_b32_e32 v16, v0
	v_mov_b32_e32 v17, v0
	v_mov_b32_e32 v18, v0
	v_mov_b32_e32 v19, v0
	v_mov_b32_e32 v20, v0
	v_mov_b32_e32 v21, v0
	v_mov_b32_e32 v22, v0
	v_mov_b32_e32 v23, v0
	v_mov_b32_e32 v32, v0
	v_mov_b32_e32 v33, v0
	v_mov_b32_e32 v34, v0
	v_mov_b32_e32 v35, v0
	v_mov_b32_e32 v36, v0
	v_mov_b32_e32 v37, v0
	v_mov_b32_e32 v38, v0
	v_mov_b32_e32 v39, v0
	v_mov_b32_e32 v48, v0
	v_mov_b32_e32 v49, v0
	v_mov_b32_e32 v50, v0
	v_mov_b32_e32 v51, v0
	v_mov_b32_e32 v52, v0
	v_mov_b32_e32 v53, v0
	v_mov_b32_e32 v54, v0
	v_mov_b32_e32 v55, v0
	v_mov_b32_e32 v8, v0
	v_mov_b32_e32 v9, v0
	v_mov_b32_e32 v10, v0
	v_mov_b32_e32 v11, v0
	v_mov_b32_e32 v12, v0
	v_mov_b32_e32 v13, v0
	v_mov_b32_e32 v14, v0
	v_mov_b32_e32 v15, v0
	v_mov_b32_e32 v24, v0
	v_mov_b32_e32 v25, v0
	v_mov_b32_e32 v26, v0
	v_mov_b32_e32 v27, v0
	v_mov_b32_e32 v28, v0
	v_mov_b32_e32 v29, v0
	v_mov_b32_e32 v30, v0
	v_mov_b32_e32 v31, v0
	v_mov_b32_e32 v40, v0
	v_mov_b32_e32 v41, v0
	v_mov_b32_e32 v42, v0
	v_mov_b32_e32 v43, v0
	v_mov_b32_e32 v44, v0
	v_mov_b32_e32 v45, v0
	v_mov_b32_e32 v46, v0
	v_mov_b32_e32 v47, v0
	v_mov_b32_e32 v56, v0
	v_mov_b32_e32 v57, v0
	v_mov_b32_e32 v58, v0
	v_mov_b32_e32 v59, v0
	v_mov_b32_e32 v60, v0
	v_mov_b32_e32 v61, v0
	v_mov_b32_e32 v62, v0
	v_mov_b32_e32 v63, v0
	v_mov_b32_e32 v64, v0
	v_mov_b32_e32 v65, v0
	v_mov_b32_e32 v66, v0
	v_mov_b32_e32 v67, v0
	v_mov_b32_e32 v68, v0
	v_mov_b32_e32 v69, v0
	v_mov_b32_e32 v70, v0
	v_mov_b32_e32 v71, v0
	v_mov_b32_e32 v80, v0
	v_mov_b32_e32 v81, v0
	v_mov_b32_e32 v82, v0
	v_mov_b32_e32 v83, v0
	v_mov_b32_e32 v84, v0
	v_mov_b32_e32 v85, v0
	v_mov_b32_e32 v86, v0
	v_mov_b32_e32 v87, v0
	v_mov_b32_e32 v96, v0
	v_mov_b32_e32 v97, v0
	v_mov_b32_e32 v98, v0
	v_mov_b32_e32 v99, v0
	v_mov_b32_e32 v100, v0
	v_mov_b32_e32 v101, v0
	v_mov_b32_e32 v102, v0
	v_mov_b32_e32 v103, v0
	v_mov_b32_e32 v112, v0
	v_mov_b32_e32 v113, v0
	v_mov_b32_e32 v114, v0
	v_mov_b32_e32 v115, v0
	v_mov_b32_e32 v116, v0
	v_mov_b32_e32 v117, v0
	v_mov_b32_e32 v118, v0
	v_mov_b32_e32 v119, v0
	v_mov_b32_e32 v72, v0
	v_mov_b32_e32 v73, v0
	v_mov_b32_e32 v74, v0
	v_mov_b32_e32 v75, v0
	v_mov_b32_e32 v76, v0
	v_mov_b32_e32 v77, v0
	v_mov_b32_e32 v78, v0
	v_mov_b32_e32 v79, v0
	v_mov_b32_e32 v88, v0
	v_mov_b32_e32 v89, v0
	v_mov_b32_e32 v90, v0
	v_mov_b32_e32 v91, v0
	v_mov_b32_e32 v92, v0
	v_mov_b32_e32 v93, v0
	v_mov_b32_e32 v94, v0
	v_mov_b32_e32 v95, v0
	v_mov_b32_e32 v104, v0
	v_mov_b32_e32 v105, v0
	v_mov_b32_e32 v106, v0
	v_mov_b32_e32 v107, v0
	v_mov_b32_e32 v108, v0
	v_mov_b32_e32 v109, v0
	v_mov_b32_e32 v110, v0
	v_mov_b32_e32 v111, v0
	v_mov_b32_e32 v120, v0
	v_mov_b32_e32 v121, v0
	v_mov_b32_e32 v122, v0
	v_mov_b32_e32 v123, v0
	v_mov_b32_e32 v124, v0
	v_mov_b32_e32 v125, v0
	v_mov_b32_e32 v126, v0
	v_mov_b32_e32 v127, v0
	.p2align 6
	s_nop 0
	s_nop 0

; #define PG8_STAGE(bufoff, gbase, voff) do { _Pragma("unroll") for (int _i = 0; _i < 2; ++_i) \
;         __builtin_amdgcn_global_load_lds((const unsigned*)((const char*)(gbase) + (voff)[_i]), (LAS unsigned*)(lds + (bufoff) + ldsw + _i * 8192), 16, 0, 0); } while (0)
; #define PG8_WAIT_V(n) asm volatile("s_waitcnt vmcnt(" #n ")" ::: "memory")
; #define PG8_BAR __builtin_amdgcn_s_barrier()
; template <class Epi, class Sched, bool ALIGN_EPI>
; __device__ __forceinline__ void gemm_phase(LAS unsigned char* lds, const Gemm g, const Sched& S, const Epi& E) {
;     ...
;     f32x4 acc[2][2][4][2];
; #pragma unroll
;     for (int a = 0; a < 2; ++a)
; #pragma unroll
;         for (int b = 0; b < 2; ++b)
; #pragma unroll
;             for (int m = 0; m < 4; ++m)
; #pragma unroll
;                 for (int n = 0; n < 2; ++n) acc[a][b][m][n] = (f32x4){0.f, 0.f, 0.f, 0.f};
;     ...
;     PG8_STAGE(PG8_SB(0, 0), cB, voffB); PG8_STAGE(PG8_SB(0, 1), cB + hB, voffB); PG8_STAGE(PG8_SA(0, 0), cA, voffA); PG8_STAGE(PG8_SA(0, 1), cA + hA, voffA);
;     if (wr == 1) PG8_BAR;
;     PG8_WAIT_V(2); PG8_BAR;
;     PG8_STAGE(PG8_SB(1, 0), cB + kstep, voffB); PG8_STAGE(PG8_SA(1, 0), cA + kstep, voffA); PG8_STAGE(PG8_SB(1, 1), cB + hB + kstep, voffB);
;     PG8_WAIT_V(6); PG8_BAR;
.LBB0_924:
	s_add_i32 m0, s22, 0x18000
	v_lshl_add_u64 v[0:1], v[0:1], 0, s[24:25]
	s_and_b32 s81, s11, 3
	s_lshl_b32 s11, s44, 6
	s_waitcnt vmcnt(2)
	s_barrier
	global_load_lds_dwordx4 v[0:1], off
	v_lshl_add_u64 v[0:1], v[2:3], 0, s[24:25]
	s_add_i32 m0, s22, 0x1a000
	s_add_i32 s90, s22, 0x8000
	s_add_i32 s91, s22, 0xa000
	global_load_lds_dwordx4 v[0:1], off
	v_lshl_add_u64 v[0:1], v[6:7], 0, s[24:25]
	s_mov_b32 m0, s90
	s_add_u32 s18, s56, 0x80080
	global_load_lds_dwordx4 v[0:1], off
	v_lshl_add_u64 v[0:1], v[4:5], 0, s[24:25]
	s_mov_b32 m0, s91
	s_addc_u32 s19, s57, 0
	global_load_lds_dwordx4 v[0:1], off
	s_add_i32 m0, s22, 0x1c000
	v_lshl_add_u64 v[0:1], s[18:19], 0, v[130:131]
	global_load_lds_dwordx4 v[0:1], off
	v_lshl_add_u64 v[0:1], s[18:19], 0, v[134:135]
	s_add_i32 m0, s22, 0x1e000
	v_mov_b32_e32 v127, 0
	global_load_lds_dwordx4 v[0:1], off
	s_waitcnt vmcnt(6)
	v_or_b32_e32 v165, s11, v145
	s_and_b64 vcc, exec, s[6:7]
	v_mov_b32_e32 v126, v127
	v_mov_b32_e32 v125, v127
	v_mov_b32_e32 v124, v127
	v_mov_b32_e32 v123, v127
	v_mov_b32_e32 v122, v127
	v_mov_b32_e32 v121, v127
	v_mov_b32_e32 v120, v127
	v_mov_b32_e32 v111, v127
	v_mov_b32_e32 v110, v127
	v_mov_b32_e32 v109, v127
	v_mov_b32_e32 v108, v127
	v_mov_b32_e32 v107, v127
	v_mov_b32_e32 v106, v127
	v_mov_b32_e32 v105, v127
	v_mov_b32_e32 v104, v127
	v_mov_b32_e32 v95, v127
	v_mov_b32_e32 v94, v127
	v_mov_b32_e32 v93, v127
	v_mov_b32_e32 v92, v127
	v_mov_b32_e32 v91, v127
	v_mov_b32_e32 v90, v127
	v_mov_b32_e32 v89, v127
	v_mov_b32_e32 v88, v127
	v_mov_b32_e32 v79, v127
	v_mov_b32_e32 v78, v127
	v_mov_b32_e32 v77, v127
	v_mov_b32_e32 v76, v127
	v_mov_b32_e32 v75, v127
	v_mov_b32_e32 v74, v127
	v_mov_b32_e32 v73, v127
	v_mov_b32_e32 v72, v127
	v_mov_b32_e32 v119, v127
	v_mov_b32_e32 v118, v127
	v_mov_b32_e32 v117, v127
	v_mov_b32_e32 v116, v127
	v_mov_b32_e32 v115, v127
	v_mov_b32_e32 v114, v127
	v_mov_b32_e32 v113, v127
	v_mov_b32_e32 v112, v127
	v_mov_b32_e32 v103, v127
	v_mov_b32_e32 v102, v127
	v_mov_b32_e32 v101, v127
	v_mov_b32_e32 v100, v127
	v_mov_b32_e32 v99, v127
	v_mov_b32_e32 v98, v127
	v_mov_b32_e32 v97, v127
	v_mov_b32_e32 v96, v127
	v_mov_b32_e32 v87, v127
	v_mov_b32_e32 v86, v127
	v_mov_b32_e32 v85, v127
	v_mov_b32_e32 v84, v127
	v_mov_b32_e32 v83, v127
	v_mov_b32_e32 v82, v127
	v_mov_b32_e32 v81, v127
	v_mov_b32_e32 v80, v127
	v_mov_b32_e32 v71, v127
	v_mov_b32_e32 v70, v127
	v_mov_b32_e32 v69, v127
	v_mov_b32_e32 v68, v127
	v_mov_b32_e32 v67, v127
	v_mov_b32_e32 v66, v127
	v_mov_b32_e32 v65, v127
	v_mov_b32_e32 v64, v127
	v_mov_b32_e32 v63, v127
	v_mov_b32_e32 v62, v127
	v_mov_b32_e32 v61, v127
	v_mov_b32_e32 v60, v127
	v_mov_b32_e32 v59, v127
	v_mov_b32_e32 v58, v127
	v_mov_b32_e32 v57, v127
	v_mov_b32_e32 v56, v127
	v_mov_b32_e32 v47, v127
	v_mov_b32_e32 v46, v127
	v_mov_b32_e32 v45, v127
	v_mov_b32_e32 v44, v127
	v_mov_b32_e32 v43, v127
	v_mov_b32_e32 v42, v127
	v_mov_b32_e32 v41, v127
	v_mov_b32_e32 v40, v127
	v_mov_b32_e32 v31, v127
	v_mov_b32_e32 v30, v127
	v_mov_b32_e32 v29, v127
	v_mov_b32_e32 v28, v127
	v_mov_b32_e32 v27, v127
	v_mov_b32_e32 v26, v127
	v_mov_b32_e32 v25, v127
	v_mov_b32_e32 v24, v127
	v_mov_b32_e32 v15, v127
	v_mov_b32_e32 v14, v127
	v_mov_b32_e32 v13, v127
	v_mov_b32_e32 v12, v127
	v_mov_b32_e32 v11, v127
	v_mov_b32_e32 v10, v127
	v_mov_b32_e32 v9, v127
	v_mov_b32_e32 v8, v127
	v_mov_b32_e32 v55, v127
	v_mov_b32_e32 v54, v127
	v_mov_b32_e32 v53, v127
	v_mov_b32_e32 v52, v127
	v_mov_b32_e32 v51, v127
	v_mov_b32_e32 v50, v127
	v_mov_b32_e32 v49, v127
	v_mov_b32_e32 v48, v127
	v_mov_b32_e32 v39, v127
	v_mov_b32_e32 v38, v127
	v_mov_b32_e32 v37, v127
	v_mov_b32_e32 v36, v127
	v_mov_b32_e32 v35, v127
	v_mov_b32_e32 v34, v127
	v_mov_b32_e32 v33, v127
	v_mov_b32_e32 v32, v127
	v_mov_b32_e32 v23, v127
	v_mov_b32_e32 v22, v127
	v_mov_b32_e32 v21, v127
	v_mov_b32_e32 v20, v127
	v_mov_b32_e32 v19, v127
	v_mov_b32_e32 v18, v127
	v_mov_b32_e32 v17, v127
	v_mov_b32_e32 v16, v127
	v_mov_b32_e32 v7, v127
	v_mov_b32_e32 v6, v127
	v_mov_b32_e32 v5, v127
	v_mov_b32_e32 v4, v127
	v_mov_b32_e32 v3, v127
	v_mov_b32_e32 v2, v127
	v_mov_b32_e32 v1, v127
	v_mov_b32_e32 v0, v127
	s_barrier
; template <class Epi, class Sched, bool ALIGN_EPI>
; __device__ __forceinline__ void gemm_phase(LAS unsigned char* lds, const Gemm g, const Sched& S, const Epi& E) {
;     const int tid = threadIdx.x, wid = __builtin_amdgcn_readfirstlane(tid >> 6), lane = tid & 63, wr = wid >> 2, wc = wid & 3, fr = lane & 15, fq = lane >> 4;
;     const int K = g.K, nt = K / BK;
;     unsigned voffA[2], voffB[2];
; #pragma unroll
;     for (int i = 0; i < 2; ++i) { int R, C; stage_rc(tid * 16 + i * 8192, R, C); const int Rb = Epi::PERM ? ((R & ~31) + perm32(R & 31)) : R;
;         voffA[i] = (unsigned)(R * g.lda + C) * 2u; voffB[i] = (unsigned)(Rb * g.ldb + C) * 2u; }
;     const size_t kstep = (size_t)(BK * 2);
;     const size_t hA = (size_t)HALF * g.lda * 2, hB = (size_t)HALF * g.ldb * 2;
;     const unsigned ldsw = (unsigned)wid * 1024u;
;     const int aoff = lds_byte(wr * 64 + fr, fq * 8), boff = lds_byte(wc * 32 + fr, fq * 8);
;     ...
;     f32x4 acc[2][2][4][2];
; #pragma unroll
;     for (int a = 0; a < 2; ++a)
; #pragma unroll
;         for (int b = 0; b < 2; ++b)
; #pragma unroll
;             for (int m = 0; m < 4; ++m)
; #pragma unroll
;                 for (int n = 0; n < 2; ++n) acc[a][b][m][n] = (f32x4){0.f, 0.f, 0.f, 0.f};
	s_cbranch_vccnz .LBB0_928
	v_lshlrev_b32_e32 v0, 6, v165
	v_lshlrev_b32_e32 v1, 2, v165
	v_and_or_b32 v0, v0, s67, v162
	v_and_b32_e32 v1, 32, v1
	s_lshl_b32 s18, s44, 13
	v_lshl_or_b32 v2, s81, 12, v163
	v_bitop3_b32 v1, v0, s18, v1 bitop3:0xde
	v_mov_b32_e32 v0, 0
	s_add_i32 s46, s70, s84
	s_add_i32 s92, s71, s84
	v_lshl_add_u64 v[146:147], v[140:141], 0, s[60:61]
	v_lshl_add_u64 v[148:149], v[142:143], 0, s[60:61]
	s_mov_b32 s62, 0
	s_mov_b64 s[60:61], 0xc580080
	v_add_u32_e32 v150, s70, v2
	v_add_u32_e32 v151, s71, v2
	v_add_u32_e32 v152, 0, v1
	s_add_i32 s44, s22, 0xc000
	s_add_i32 s45, s22, 0xe000
	s_add_i32 s47, s46, 0x2000
	s_add_i32 s93, s92, 0x2000
	v_add_u32_e32 v153, s74, v2
	v_add_u32_e32 v154, s75, v2
	v_mov_b32_e32 v1, v0
	v_mov_b32_e32 v2, v0
	v_mov_b32_e32 v3, v0
	v_mov_b32_e32 v4, v0
	v_mov_b32_e32 v5, v0
	v_mov_b32_e32 v6, v0
	v_mov_b32_e32 v7, v0
	v_mov_b32_e32 v16, v0
	v_mov_b32_e32 v17, v0
	v_mov_b32_e32 v18, v0
	v_mov_b32_e32 v19, v0
	v_mov_b32_e32 v20, v0
	v_mov_b32_e32 v21, v0
	v_mov_b32_e32 v22, v0
	v_mov_b32_e32 v23, v0
	v_mov_b32_e32 v32, v0
	v_mov_b32_e32 v33, v0
	v_mov_b32_e32 v34, v0
	v_mov_b32_e32 v35, v0
	v_mov_b32_e32 v36, v0
	v_mov_b32_e32 v37, v0
	v_mov_b32_e32 v38, v0
	v_mov_b32_e32 v39, v0
	v_mov_b32_e32 v48, v0
	v_mov_b32_e32 v49, v0
	v_mov_b32_e32 v50, v0
	v_mov_b32_e32 v51, v0
	v_mov_b32_e32 v52, v0
	v_mov_b32_e32 v53, v0
	v_mov_b32_e32 v54, v0
	v_mov_b32_e32 v55, v0
	v_mov_b32_e32 v8, v0
	v_mov_b32_e32 v9, v0
	v_mov_b32_e32 v10, v0
	v_mov_b32_e32 v11, v0
	v_mov_b32_e32 v12, v0
	v_mov_b32_e32 v13, v0
	v_mov_b32_e32 v14, v0
	v_mov_b32_e32 v15, v0
	v_mov_b32_e32 v24, v0
	v_mov_b32_e32 v25, v0
	v_mov_b32_e32 v26, v0
	v_mov_b32_e32 v27, v0
	v_mov_b32_e32 v28, v0
	v_mov_b32_e32 v29, v0
	v_mov_b32_e32 v30, v0
	v_mov_b32_e32 v31, v0
	v_mov_b32_e32 v40, v0
	v_mov_b32_e32 v41, v0
	v_mov_b32_e32 v42, v0
	v_mov_b32_e32 v43, v0
	v_mov_b32_e32 v44, v0
	v_mov_b32_e32 v45, v0
	v_mov_b32_e32 v46, v0
	v_mov_b32_e32 v47, v0
	v_mov_b32_e32 v56, v0
	v_mov_b32_e32 v57, v0
	v_mov_b32_e32 v58, v0
	v_mov_b32_e32 v59, v0
	v_mov_b32_e32 v60, v0
	v_mov_b32_e32 v61, v0
	v_mov_b32_e32 v62, v0
	v_mov_b32_e32 v63, v0
	v_mov_b32_e32 v64, v0
	v_mov_b32_e32 v65, v0
	v_mov_b32_e32 v66, v0
	v_mov_b32_e32 v67, v0
	v_mov_b32_e32 v68, v0
	v_mov_b32_e32 v69, v0
	v_mov_b32_e32 v70, v0
	v_mov_b32_e32 v71, v0
	v_mov_b32_e32 v80, v0
	v_mov_b32_e32 v81, v0
	v_mov_b32_e32 v82, v0
	v_mov_b32_e32 v83, v0
	v_mov_b32_e32 v84, v0
	v_mov_b32_e32 v85, v0
	v_mov_b32_e32 v86, v0
	v_mov_b32_e32 v87, v0
	v_mov_b32_e32 v96, v0
	v_mov_b32_e32 v97, v0
	v_mov_b32_e32 v98, v0
	v_mov_b32_e32 v99, v0
	v_mov_b32_e32 v100, v0
	v_mov_b32_e32 v101, v0
	v_mov_b32_e32 v102, v0
	v_mov_b32_e32 v103, v0
	v_mov_b32_e32 v112, v0
	v_mov_b32_e32 v113, v0
	v_mov_b32_e32 v114, v0
	v_mov_b32_e32 v115, v0
	v_mov_b32_e32 v116, v0
	v_mov_b32_e32 v117, v0
	v_mov_b32_e32 v118, v0
	v_mov_b32_e32 v119, v0
	v_mov_b32_e32 v72, v0
	v_mov_b32_e32 v73, v0
	v_mov_b32_e32 v74, v0
	v_mov_b32_e32 v75, v0
	v_mov_b32_e32 v76, v0
	v_mov_b32_e32 v77, v0
	v_mov_b32_e32 v78, v0
	v_mov_b32_e32 v79, v0
	v_mov_b32_e32 v88, v0
	v_mov_b32_e32 v89, v0
	v_mov_b32_e32 v90, v0
	v_mov_b32_e32 v91, v0
	v_mov_b32_e32 v92, v0
	v_mov_b32_e32 v93, v0
	v_mov_b32_e32 v94, v0
	v_mov_b32_e32 v95, v0
	v_mov_b32_e32 v104, v0
	v_mov_b32_e32 v105, v0
	v_mov_b32_e32 v106, v0
	v_mov_b32_e32 v107, v0
	v_mov_b32_e32 v108, v0
	v_mov_b32_e32 v109, v0
	v_mov_b32_e32 v110, v0
	v_mov_b32_e32 v111, v0
	v_mov_b32_e32 v120, v0
	v_mov_b32_e32 v121, v0
	v_mov_b32_e32 v122, v0
	v_mov_b32_e32 v123, v0
	v_mov_b32_e32 v124, v0
	v_mov_b32_e32 v125, v0
	v_mov_b32_e32 v126, v0
	v_mov_b32_e32 v127, v0
	.p2align 6
	s_nop 0
	s_nop 0

; #define PG8_STAGE(bufoff, gbase, voff) do { _Pragma("unroll") for (int _i = 0; _i < 2; ++_i) \
;         __builtin_amdgcn_global_load_lds((const unsigned*)((const char*)(gbase) + (voff)[_i]), (LAS unsigned*)(lds + (bufoff) + ldsw + _i * 8192), 16, 0, 0); } while (0)
; #define PG8_WAIT_V(n) asm volatile("s_waitcnt vmcnt(" #n ")" ::: "memory")
; #define PG8_BAR __builtin_amdgcn_s_barrier()
; template <class Epi, class Sched, bool ALIGN_EPI>
; __device__ __forceinline__ void gemm_phase(LAS unsigned char* lds, const Gemm g, const Sched& S, const Epi& E) {
;     ...
;     f32x4 acc[2][2][4][2];
; #pragma unroll
;     for (int a = 0; a < 2; ++a)
; #pragma unroll
;         for (int b = 0; b < 2; ++b)
; #pragma unroll
;             for (int m = 0; m < 4; ++m)
; #pragma unroll
;                 for (int n = 0; n < 2; ++n) acc[a][b][m][n] = (f32x4){0.f, 0.f, 0.f, 0.f};
;     ...
;     PG8_STAGE(PG8_SB(0, 0), cB, voffB); PG8_STAGE(PG8_SB(0, 1), cB + hB, voffB); PG8_STAGE(PG8_SA(0, 0), cA, voffA); PG8_STAGE(PG8_SA(0, 1), cA + hA, voffA);
;     if (wr == 1) PG8_BAR;
;     PG8_WAIT_V(2); PG8_BAR;
;     PG8_STAGE(PG8_SB(1, 0), cB + kstep, voffB); PG8_STAGE(PG8_SA(1, 0), cA + kstep, voffA); PG8_STAGE(PG8_SB(1, 1), cB + hB + kstep, voffB);
;     PG8_WAIT_V(6); PG8_BAR;
.LBB0_953:
	s_lshl_b32 s4, s39, 5
	s_add_i32 m0, s23, 0x18000
	v_lshl_add_u64 v[0:1], v[0:1], 0, s[6:7]
	s_and_b32 s65, s4, 0x60
	s_waitcnt vmcnt(2)
	s_barrier
	global_load_lds_dwordx4 v[0:1], off
	v_lshl_add_u64 v[0:1], v[2:3], 0, s[6:7]
	s_add_i32 m0, s23, 0x1a000
	s_add_i32 s70, s23, 0x8000
	s_add_i32 s71, s23, 0xa000
	global_load_lds_dwordx4 v[0:1], off
	v_lshl_add_u64 v[0:1], v[6:7], 0, s[6:7]
	s_mov_b32 m0, s70
	s_add_u32 s18, s24, 0x100080
	global_load_lds_dwordx4 v[0:1], off
	v_lshl_add_u64 v[0:1], v[4:5], 0, s[6:7]
	s_mov_b32 m0, s71
	s_addc_u32 s19, s25, 0
	global_load_lds_dwordx4 v[0:1], off
	s_add_i32 m0, s23, 0x1c000
	v_lshl_add_u64 v[0:1], s[18:19], 0, v[130:131]
	global_load_lds_dwordx4 v[0:1], off
	v_lshl_add_u64 v[0:1], s[18:19], 0, v[134:135]
	s_add_i32 m0, s23, 0x1e000
	v_mov_b32_e32 v127, 0
	global_load_lds_dwordx4 v[0:1], off
	s_waitcnt vmcnt(6)
	v_lshl_or_b32 v136, s38, 6, v146
	s_and_b64 vcc, exec, s[2:3]
	v_mov_b32_e32 v126, v127
	v_mov_b32_e32 v125, v127
	v_mov_b32_e32 v124, v127
	v_mov_b32_e32 v123, v127
	v_mov_b32_e32 v122, v127
	v_mov_b32_e32 v121, v127
	v_mov_b32_e32 v120, v127
	v_mov_b32_e32 v111, v127
	v_mov_b32_e32 v110, v127
	v_mov_b32_e32 v109, v127
	v_mov_b32_e32 v108, v127
	v_mov_b32_e32 v107, v127
	v_mov_b32_e32 v106, v127
	v_mov_b32_e32 v105, v127
	v_mov_b32_e32 v104, v127
	v_mov_b32_e32 v95, v127
	v_mov_b32_e32 v94, v127
	v_mov_b32_e32 v93, v127
	v_mov_b32_e32 v92, v127
	v_mov_b32_e32 v91, v127
	v_mov_b32_e32 v90, v127
	v_mov_b32_e32 v89, v127
	v_mov_b32_e32 v88, v127
	v_mov_b32_e32 v79, v127
	v_mov_b32_e32 v78, v127
	v_mov_b32_e32 v77, v127
	v_mov_b32_e32 v76, v127
	v_mov_b32_e32 v75, v127
	v_mov_b32_e32 v74, v127
	v_mov_b32_e32 v73, v127
	v_mov_b32_e32 v72, v127
	v_mov_b32_e32 v119, v127
	v_mov_b32_e32 v118, v127
	v_mov_b32_e32 v117, v127
	v_mov_b32_e32 v116, v127
	v_mov_b32_e32 v115, v127
	v_mov_b32_e32 v114, v127
	v_mov_b32_e32 v113, v127
	v_mov_b32_e32 v112, v127
	v_mov_b32_e32 v103, v127
	v_mov_b32_e32 v102, v127
	v_mov_b32_e32 v101, v127
	v_mov_b32_e32 v100, v127
	v_mov_b32_e32 v99, v127
	v_mov_b32_e32 v98, v127
	v_mov_b32_e32 v97, v127
	v_mov_b32_e32 v96, v127
	v_mov_b32_e32 v87, v127
	v_mov_b32_e32 v86, v127
	v_mov_b32_e32 v85, v127
	v_mov_b32_e32 v84, v127
	v_mov_b32_e32 v83, v127
	v_mov_b32_e32 v82, v127
	v_mov_b32_e32 v81, v127
	v_mov_b32_e32 v80, v127
	v_mov_b32_e32 v71, v127
	v_mov_b32_e32 v70, v127
	v_mov_b32_e32 v69, v127
	v_mov_b32_e32 v68, v127
	v_mov_b32_e32 v67, v127
	v_mov_b32_e32 v66, v127
	v_mov_b32_e32 v65, v127
	v_mov_b32_e32 v64, v127
	v_mov_b32_e32 v63, v127
	v_mov_b32_e32 v62, v127
	v_mov_b32_e32 v61, v127
	v_mov_b32_e32 v60, v127
	v_mov_b32_e32 v59, v127
	v_mov_b32_e32 v58, v127
	v_mov_b32_e32 v57, v127
	v_mov_b32_e32 v56, v127
	v_mov_b32_e32 v47, v127
	v_mov_b32_e32 v46, v127
	v_mov_b32_e32 v45, v127
	v_mov_b32_e32 v44, v127
	v_mov_b32_e32 v43, v127
	v_mov_b32_e32 v42, v127
	v_mov_b32_e32 v41, v127
	v_mov_b32_e32 v40, v127
	v_mov_b32_e32 v31, v127
	v_mov_b32_e32 v30, v127
	v_mov_b32_e32 v29, v127
	v_mov_b32_e32 v28, v127
	v_mov_b32_e32 v27, v127
	v_mov_b32_e32 v26, v127
	v_mov_b32_e32 v25, v127
	v_mov_b32_e32 v24, v127
	v_mov_b32_e32 v15, v127
	v_mov_b32_e32 v14, v127
	v_mov_b32_e32 v13, v127
	v_mov_b32_e32 v12, v127
	v_mov_b32_e32 v11, v127
	v_mov_b32_e32 v10, v127
	v_mov_b32_e32 v9, v127
	v_mov_b32_e32 v8, v127
	v_mov_b32_e32 v55, v127
	v_mov_b32_e32 v54, v127
	v_mov_b32_e32 v53, v127
	v_mov_b32_e32 v52, v127
	v_mov_b32_e32 v51, v127
	v_mov_b32_e32 v50, v127
	v_mov_b32_e32 v49, v127
	v_mov_b32_e32 v48, v127
	v_mov_b32_e32 v39, v127
	v_mov_b32_e32 v38, v127
	v_mov_b32_e32 v37, v127
	v_mov_b32_e32 v36, v127
	v_mov_b32_e32 v35, v127
	v_mov_b32_e32 v34, v127
	v_mov_b32_e32 v33, v127
	v_mov_b32_e32 v32, v127
	v_mov_b32_e32 v23, v127
	v_mov_b32_e32 v22, v127
	v_mov_b32_e32 v21, v127
	v_mov_b32_e32 v20, v127
	v_mov_b32_e32 v19, v127
	v_mov_b32_e32 v18, v127
	v_mov_b32_e32 v17, v127
	v_mov_b32_e32 v16, v127
	v_mov_b32_e32 v7, v127
	v_mov_b32_e32 v6, v127
	v_mov_b32_e32 v5, v127
	v_mov_b32_e32 v4, v127
	v_mov_b32_e32 v3, v127
	v_mov_b32_e32 v2, v127
	v_mov_b32_e32 v1, v127
	v_mov_b32_e32 v0, v127
	s_barrier
; template <class Epi, class Sched, bool ALIGN_EPI>
; __device__ __forceinline__ void gemm_phase(LAS unsigned char* lds, const Gemm g, const Sched& S, const Epi& E) {
;     const int tid = threadIdx.x, wid = __builtin_amdgcn_readfirstlane(tid >> 6), lane = tid & 63, wr = wid >> 2, wc = wid & 3, fr = lane & 15, fq = lane >> 4;
;     const int K = g.K, nt = K / BK;
;     unsigned voffA[2], voffB[2];
; #pragma unroll
;     for (int i = 0; i < 2; ++i) { int R, C; stage_rc(tid * 16 + i * 8192, R, C); const int Rb = Epi::PERM ? ((R & ~31) + perm32(R & 31)) : R;
;         voffA[i] = (unsigned)(R * g.lda + C) * 2u; voffB[i] = (unsigned)(Rb * g.ldb + C) * 2u; }
;     const size_t kstep = (size_t)(BK * 2);
;     const size_t hA = (size_t)HALF * g.lda * 2, hB = (size_t)HALF * g.ldb * 2;
;     const unsigned ldsw = (unsigned)wid * 1024u;
;     const int aoff = lds_byte(wr * 64 + fr, fq * 8), boff = lds_byte(wc * 32 + fr, fq * 8);
;     ...
;     f32x4 acc[2][2][4][2];
; #pragma unroll
;     for (int a = 0; a < 2; ++a)
; #pragma unroll
;         for (int b = 0; b < 2; ++b)
; #pragma unroll
;             for (int m = 0; m < 4; ++m)
; #pragma unroll
;                 for (int n = 0; n < 2; ++n) acc[a][b][m][n] = (f32x4){0.f, 0.f, 0.f, 0.f};
	s_cbranch_vccnz .LBB0_956
	s_lshr_b32 s4, s54, 3
	s_and_b32 s18, s58, 7
	s_and_b32 s4, s4, 3
	s_lshl_b32 s18, s18, 20
	s_lshl_b32 s4, s4, 10
	s_or_b32 s4, s18, s4
	v_lshlrev_b32_e32 v0, 6, v136
	v_lshlrev_b32_e32 v1, 2, v136
	v_lshl_add_u64 v[142:143], v[138:139], 0, s[4:5]
	v_lshl_add_u64 v[144:145], v[140:141], 0, s[4:5]
	v_and_or_b32 v0, v0, s55, v148
	v_and_b32_e32 v1, 32, v1
	s_lshl_b32 s4, s38, 13
	v_lshl_or_b32 v150, s65, 7, v149
	v_bitop3_b32 v1, v0, s4, v1 bitop3:0xde
	v_mov_b32_e32 v0, 0
	s_add_i32 s45, s59, s11
	s_add_i32 s47, s60, s11
	s_mov_b32 s40, 0
	s_mov_b64 s[38:39], 0xb480080
	v_add_u32_e32 v151, 0, v1
	v_add_u32_e32 v152, s59, v150
	v_add_u32_e32 v153, s60, v150
	s_add_i32 s4, s23, 0xc000
	s_add_i32 s44, s23, 0xe000
	s_add_i32 s46, s45, 0x2000
	s_add_i32 s74, s47, 0x2000
	v_add_u32_e32 v154, s61, v150
	v_mov_b32_e32 v1, v0
	v_mov_b32_e32 v2, v0
	v_mov_b32_e32 v3, v0
	v_mov_b32_e32 v4, v0
	v_mov_b32_e32 v5, v0
	v_mov_b32_e32 v6, v0
	v_mov_b32_e32 v7, v0
	v_mov_b32_e32 v16, v0
	v_mov_b32_e32 v17, v0
	v_mov_b32_e32 v18, v0
	v_mov_b32_e32 v19, v0
	v_mov_b32_e32 v20, v0
	v_mov_b32_e32 v21, v0
	v_mov_b32_e32 v22, v0
	v_mov_b32_e32 v23, v0
	v_mov_b32_e32 v32, v0
	v_mov_b32_e32 v33, v0
	v_mov_b32_e32 v34, v0
	v_mov_b32_e32 v35, v0
	v_mov_b32_e32 v36, v0
	v_mov_b32_e32 v37, v0
	v_mov_b32_e32 v38, v0
	v_mov_b32_e32 v39, v0
	v_mov_b32_e32 v48, v0
	v_mov_b32_e32 v49, v0
	v_mov_b32_e32 v50, v0
	v_mov_b32_e32 v51, v0
	v_mov_b32_e32 v52, v0
	v_mov_b32_e32 v53, v0
	v_mov_b32_e32 v54, v0
	v_mov_b32_e32 v55, v0
	v_mov_b32_e32 v8, v0
	v_mov_b32_e32 v9, v0
	v_mov_b32_e32 v10, v0
	v_mov_b32_e32 v11, v0
	v_mov_b32_e32 v12, v0
	v_mov_b32_e32 v13, v0
	v_mov_b32_e32 v14, v0
	v_mov_b32_e32 v15, v0
	v_mov_b32_e32 v24, v0
	v_mov_b32_e32 v25, v0
	v_mov_b32_e32 v26, v0
	v_mov_b32_e32 v27, v0
	v_mov_b32_e32 v28, v0
	v_mov_b32_e32 v29, v0
	v_mov_b32_e32 v30, v0
	v_mov_b32_e32 v31, v0
	v_mov_b32_e32 v40, v0
	v_mov_b32_e32 v41, v0
	v_mov_b32_e32 v42, v0
	v_mov_b32_e32 v43, v0
	v_mov_b32_e32 v44, v0
	v_mov_b32_e32 v45, v0
	v_mov_b32_e32 v46, v0
	v_mov_b32_e32 v47, v0
	v_mov_b32_e32 v56, v0
	v_mov_b32_e32 v57, v0
	v_mov_b32_e32 v58, v0
	v_mov_b32_e32 v59, v0
	v_mov_b32_e32 v60, v0
	v_mov_b32_e32 v61, v0
	v_mov_b32_e32 v62, v0
	v_mov_b32_e32 v63, v0
	v_mov_b32_e32 v64, v0
	v_mov_b32_e32 v65, v0
	v_mov_b32_e32 v66, v0
	v_mov_b32_e32 v67, v0
	v_mov_b32_e32 v68, v0
	v_mov_b32_e32 v69, v0
	v_mov_b32_e32 v70, v0
	v_mov_b32_e32 v71, v0
	v_mov_b32_e32 v80, v0
	v_mov_b32_e32 v81, v0
	v_mov_b32_e32 v82, v0
	v_mov_b32_e32 v83, v0
	v_mov_b32_e32 v84, v0
	v_mov_b32_e32 v85, v0
	v_mov_b32_e32 v86, v0
	v_mov_b32_e32 v87, v0
	v_mov_b32_e32 v96, v0
	v_mov_b32_e32 v97, v0
	v_mov_b32_e32 v98, v0
	v_mov_b32_e32 v99, v0
	v_mov_b32_e32 v100, v0
	v_mov_b32_e32 v101, v0
	v_mov_b32_e32 v102, v0
	v_mov_b32_e32 v103, v0
	v_mov_b32_e32 v112, v0
	v_mov_b32_e32 v113, v0
	v_mov_b32_e32 v114, v0
	v_mov_b32_e32 v115, v0
	v_mov_b32_e32 v116, v0
	v_mov_b32_e32 v117, v0
	v_mov_b32_e32 v118, v0
	v_mov_b32_e32 v119, v0
	v_mov_b32_e32 v72, v0
	v_mov_b32_e32 v73, v0
	v_mov_b32_e32 v74, v0
	v_mov_b32_e32 v75, v0
	v_mov_b32_e32 v76, v0
	v_mov_b32_e32 v77, v0
	v_mov_b32_e32 v78, v0
	v_mov_b32_e32 v79, v0
	v_mov_b32_e32 v88, v0
	v_mov_b32_e32 v89, v0
	v_mov_b32_e32 v90, v0
	v_mov_b32_e32 v91, v0
	v_mov_b32_e32 v92, v0
	v_mov_b32_e32 v93, v0
	v_mov_b32_e32 v94, v0
	v_mov_b32_e32 v95, v0
	v_mov_b32_e32 v104, v0
	v_mov_b32_e32 v105, v0
	v_mov_b32_e32 v106, v0
	v_mov_b32_e32 v107, v0
	v_mov_b32_e32 v108, v0
	v_mov_b32_e32 v109, v0
	v_mov_b32_e32 v110, v0
	v_mov_b32_e32 v111, v0
	v_mov_b32_e32 v120, v0
	v_mov_b32_e32 v121, v0
	v_mov_b32_e32 v122, v0
	v_mov_b32_e32 v123, v0
	v_mov_b32_e32 v124, v0
	v_mov_b32_e32 v125, v0
	v_mov_b32_e32 v126, v0
	v_mov_b32_e32 v127, v0
	.p2align 6
	s_nop 0
	s_nop 0

;     __device__ bool next(int i, Unit& u) const { int pm, pn; if (!so.next(i, pm, pn)) return false; u.pm = pm; u.pn = pn; u.aoff = (unsigned)pm * BM * lda; u.boff = (unsigned)pn * BM * ldb; return true; }
;     __device__ __forceinline__ bool next(int i, Unit& u) const { int pm, pn; if (!so.next(i, pm, pn)) return false; u.pm = pm; u.pn = pn; u.aoff = (unsigned)pm * BM * lda; u.boff = (unsigned)(pm >> 4) * bstride + (unsigned)pn * BM * ldb; return true; }
;     __device__ __forceinline__ bool next(int i, Unit& u) const { int pm, pn; if (!so.next(i, pm, pn)) return false; u.pm = pm; u.pn = ((pn & 12) == 4 || (pn & 12) == 8) ? (pn ^ 12) : pn; u.aoff = (unsigned)pm * BM * lda; u.boff = (unsigned)pn * BM * ldb; return true; }
; template <class Epi, class Sched, bool ALIGN_EPI>
; __device__ __forceinline__ void gemm_phase(LAS unsigned char* lds, const Gemm g, const Sched& S, const Epi& E) {
;     ...
;         const bool has_next = S.next(ui + 1, nxt);
;         const char* nA = has_next ? (const char*)g.A + (size_t)nxt.aoff * 2 : cA; const char* nB = has_next ? (const char*)g.Bt + (size_t)nxt.boff * 2 : cB;
;     ...
; #pragma unroll
;         for (int a = 0; a < 2; ++a)
; #pragma unroll
;             for (int b = 0; b < 2; ++b)
; #pragma unroll
;                 for (int m = 0; m < 4; ++m)
; #pragma unroll
;                     for (int n = 0; n < 2; ++n) acc[a][b][m][n] = (f32x4){0.f, 0.f, 0.f, 0.f};
.LBB0_1063:
	s_lshl_b64 s[18:19], s[20:21], 1
	s_add_u32 s40, s36, s18
	s_mov_b32 s39, s21
	s_addc_u32 s41, s37, s19
	s_lshl_b64 s[18:19], s[38:39], 1
	s_add_u32 s42, s72, s18
	v_mov_b32_e32 v127, 0
	s_addc_u32 s43, s73, s19
	s_andn2_b64 vcc, exec, s[26:27]
	v_mov_b32_e32 v126, v127
	v_mov_b32_e32 v125, v127
	v_mov_b32_e32 v124, v127
	v_mov_b32_e32 v123, v127
	v_mov_b32_e32 v122, v127
	v_mov_b32_e32 v121, v127
	v_mov_b32_e32 v120, v127
	v_mov_b32_e32 v111, v127
	v_mov_b32_e32 v110, v127
	v_mov_b32_e32 v109, v127
	v_mov_b32_e32 v108, v127
	v_mov_b32_e32 v107, v127
	v_mov_b32_e32 v106, v127
	v_mov_b32_e32 v105, v127
	v_mov_b32_e32 v104, v127
	v_mov_b32_e32 v95, v127
	v_mov_b32_e32 v94, v127
	v_mov_b32_e32 v93, v127
	v_mov_b32_e32 v92, v127
	v_mov_b32_e32 v91, v127
	v_mov_b32_e32 v90, v127
	v_mov_b32_e32 v89, v127
	v_mov_b32_e32 v88, v127
	v_mov_b32_e32 v79, v127
	v_mov_b32_e32 v78, v127
	v_mov_b32_e32 v77, v127
	v_mov_b32_e32 v76, v127
	v_mov_b32_e32 v75, v127
	v_mov_b32_e32 v74, v127
	v_mov_b32_e32 v73, v127
	v_mov_b32_e32 v72, v127
	v_mov_b32_e32 v119, v127
	v_mov_b32_e32 v118, v127
	v_mov_b32_e32 v117, v127
	v_mov_b32_e32 v116, v127
	v_mov_b32_e32 v115, v127
	v_mov_b32_e32 v114, v127
	v_mov_b32_e32 v113, v127
	v_mov_b32_e32 v112, v127
	v_mov_b32_e32 v103, v127
	v_mov_b32_e32 v102, v127
	v_mov_b32_e32 v101, v127
	v_mov_b32_e32 v100, v127
	v_mov_b32_e32 v99, v127
	v_mov_b32_e32 v98, v127
	v_mov_b32_e32 v97, v127
	v_mov_b32_e32 v96, v127
	v_mov_b32_e32 v87, v127
	v_mov_b32_e32 v86, v127
	v_mov_b32_e32 v85, v127
	v_mov_b32_e32 v84, v127
	v_mov_b32_e32 v83, v127
	v_mov_b32_e32 v82, v127
	v_mov_b32_e32 v81, v127
	v_mov_b32_e32 v80, v127
	v_mov_b32_e32 v71, v127
	v_mov_b32_e32 v70, v127
	v_mov_b32_e32 v69, v127
	v_mov_b32_e32 v68, v127
	v_mov_b32_e32 v67, v127
	v_mov_b32_e32 v66, v127
	v_mov_b32_e32 v65, v127
	v_mov_b32_e32 v64, v127
	v_mov_b32_e32 v63, v127
	v_mov_b32_e32 v62, v127
	v_mov_b32_e32 v61, v127
	v_mov_b32_e32 v60, v127
	v_mov_b32_e32 v59, v127
	v_mov_b32_e32 v58, v127
	v_mov_b32_e32 v57, v127
	v_mov_b32_e32 v56, v127
	v_mov_b32_e32 v47, v127
	v_mov_b32_e32 v46, v127
	v_mov_b32_e32 v45, v127
	v_mov_b32_e32 v44, v127
	v_mov_b32_e32 v43, v127
	v_mov_b32_e32 v42, v127
	v_mov_b32_e32 v41, v127
	v_mov_b32_e32 v40, v127
	v_mov_b32_e32 v31, v127
	v_mov_b32_e32 v30, v127
	v_mov_b32_e32 v29, v127
	v_mov_b32_e32 v28, v127
	v_mov_b32_e32 v27, v127
	v_mov_b32_e32 v26, v127
	v_mov_b32_e32 v25, v127
	v_mov_b32_e32 v24, v127
	v_mov_b32_e32 v15, v127
	v_mov_b32_e32 v14, v127
	v_mov_b32_e32 v13, v127
	v_mov_b32_e32 v12, v127
	v_mov_b32_e32 v11, v127
	v_mov_b32_e32 v10, v127
	v_mov_b32_e32 v9, v127
	v_mov_b32_e32 v8, v127
	v_mov_b32_e32 v55, v127
	v_mov_b32_e32 v54, v127
	v_mov_b32_e32 v53, v127
	v_mov_b32_e32 v52, v127
	v_mov_b32_e32 v51, v127
	v_mov_b32_e32 v50, v127
	v_mov_b32_e32 v49, v127
	v_mov_b32_e32 v48, v127
	v_mov_b32_e32 v39, v127
	v_mov_b32_e32 v38, v127
	v_mov_b32_e32 v37, v127
	v_mov_b32_e32 v36, v127
	v_mov_b32_e32 v35, v127
	v_mov_b32_e32 v34, v127
	v_mov_b32_e32 v33, v127
	v_mov_b32_e32 v32, v127
	v_mov_b32_e32 v23, v127
	v_mov_b32_e32 v22, v127
	v_mov_b32_e32 v21, v127
	v_mov_b32_e32 v20, v127
	v_mov_b32_e32 v19, v127
	v_mov_b32_e32 v18, v127
	v_mov_b32_e32 v17, v127
	v_mov_b32_e32 v16, v127
	v_mov_b32_e32 v7, v127
	v_mov_b32_e32 v6, v127
	v_mov_b32_e32 v5, v127
	v_mov_b32_e32 v4, v127
	v_mov_b32_e32 v3, v127
	v_mov_b32_e32 v2, v127
	s_waitcnt lgkmcnt(0)
	v_mov_b32_e32 v1, v127
	v_mov_b32_e32 v0, v127
	s_cbranch_vccnz .LBB0_1066
	s_and_b64 s[18:19], s[4:5], exec
	s_cselect_b32 s11, s41, s53
	s_cselect_b32 s39, s40, s52
	s_cselect_b32 s80, s43, s55
	s_cselect_b32 s81, s42, s54
	s_add_u32 s52, s52, 0x40080
	s_addc_u32 s53, s53, 0
	s_add_u32 s44, s54, 0x100
	v_mov_b32_e32 v0, 0
	s_addc_u32 s45, s55, 0
	s_mov_b32 s46, 0
	v_mov_b32_e32 v1, v0
	v_mov_b32_e32 v2, v0
	v_mov_b32_e32 v3, v0
	v_mov_b32_e32 v4, v0
	v_mov_b32_e32 v5, v0
	v_mov_b32_e32 v6, v0
	v_mov_b32_e32 v7, v0
	v_mov_b32_e32 v16, v0
	v_mov_b32_e32 v17, v0
	v_mov_b32_e32 v18, v0
	v_mov_b32_e32 v19, v0
	v_mov_b32_e32 v20, v0
	v_mov_b32_e32 v21, v0
	v_mov_b32_e32 v22, v0
	v_mov_b32_e32 v23, v0
	v_mov_b32_e32 v32, v0
	v_mov_b32_e32 v33, v0
	v_mov_b32_e32 v34, v0
	v_mov_b32_e32 v35, v0
	v_mov_b32_e32 v36, v0
	v_mov_b32_e32 v37, v0
	v_mov_b32_e32 v38, v0
	v_mov_b32_e32 v39, v0
	v_mov_b32_e32 v48, v0
	v_mov_b32_e32 v49, v0
	v_mov_b32_e32 v50, v0
	v_mov_b32_e32 v51, v0
	v_mov_b32_e32 v52, v0
	v_mov_b32_e32 v53, v0
	v_mov_b32_e32 v54, v0
	v_mov_b32_e32 v55, v0
	v_mov_b32_e32 v8, v0
	v_mov_b32_e32 v9, v0
	v_mov_b32_e32 v10, v0
	v_mov_b32_e32 v11, v0
	v_mov_b32_e32 v12, v0
	v_mov_b32_e32 v13, v0
	v_mov_b32_e32 v14, v0
	v_mov_b32_e32 v15, v0
	v_mov_b32_e32 v24, v0
	v_mov_b32_e32 v25, v0
	v_mov_b32_e32 v26, v0
	v_mov_b32_e32 v27, v0
	v_mov_b32_e32 v28, v0
	v_mov_b32_e32 v29, v0
	v_mov_b32_e32 v30, v0
	v_mov_b32_e32 v31, v0
	v_mov_b32_e32 v40, v0
	v_mov_b32_e32 v41, v0
	v_mov_b32_e32 v42, v0
	v_mov_b32_e32 v43, v0
	v_mov_b32_e32 v44, v0
	v_mov_b32_e32 v45, v0
	v_mov_b32_e32 v46, v0
	v_mov_b32_e32 v47, v0
	v_mov_b32_e32 v56, v0
	v_mov_b32_e32 v57, v0
	v_mov_b32_e32 v58, v0
	v_mov_b32_e32 v59, v0
	v_mov_b32_e32 v60, v0
	v_mov_b32_e32 v61, v0
	v_mov_b32_e32 v62, v0
	v_mov_b32_e32 v63, v0
	v_mov_b32_e32 v64, v0
	v_mov_b32_e32 v65, v0
	v_mov_b32_e32 v66, v0
	v_mov_b32_e32 v67, v0
	v_mov_b32_e32 v68, v0
	v_mov_b32_e32 v69, v0
	v_mov_b32_e32 v70, v0
	v_mov_b32_e32 v71, v0
	v_mov_b32_e32 v80, v0
	v_mov_b32_e32 v81, v0
	v_mov_b32_e32 v82, v0
	v_mov_b32_e32 v83, v0
	v_mov_b32_e32 v84, v0
	v_mov_b32_e32 v85, v0
	v_mov_b32_e32 v86, v0
	v_mov_b32_e32 v87, v0
	v_mov_b32_e32 v96, v0
	v_mov_b32_e32 v97, v0
	v_mov_b32_e32 v98, v0
	v_mov_b32_e32 v99, v0
	v_mov_b32_e32 v100, v0
	v_mov_b32_e32 v101, v0
	v_mov_b32_e32 v102, v0
	v_mov_b32_e32 v103, v0
	v_mov_b32_e32 v112, v0
	v_mov_b32_e32 v113, v0
	v_mov_b32_e32 v114, v0
	v_mov_b32_e32 v115, v0
	v_mov_b32_e32 v116, v0
	v_mov_b32_e32 v117, v0
	v_mov_b32_e32 v118, v0
	v_mov_b32_e32 v119, v0
	v_mov_b32_e32 v72, v0
	v_mov_b32_e32 v73, v0
	v_mov_b32_e32 v74, v0
	v_mov_b32_e32 v75, v0
	v_mov_b32_e32 v76, v0
	v_mov_b32_e32 v77, v0
	v_mov_b32_e32 v78, v0
	v_mov_b32_e32 v79, v0
	v_mov_b32_e32 v88, v0
	v_mov_b32_e32 v89, v0
	v_mov_b32_e32 v90, v0
	v_mov_b32_e32 v91, v0
	v_mov_b32_e32 v92, v0
	v_mov_b32_e32 v93, v0
	v_mov_b32_e32 v94, v0
	v_mov_b32_e32 v95, v0
	v_mov_b32_e32 v104, v0
	v_mov_b32_e32 v105, v0
	v_mov_b32_e32 v106, v0
	v_mov_b32_e32 v107, v0
	v_mov_b32_e32 v108, v0
	v_mov_b32_e32 v109, v0
	v_mov_b32_e32 v110, v0
	v_mov_b32_e32 v111, v0
	v_mov_b32_e32 v120, v0
	v_mov_b32_e32 v121, v0
	v_mov_b32_e32 v122, v0
	v_mov_b32_e32 v123, v0
	v_mov_b32_e32 v124, v0
	v_mov_b32_e32 v125, v0
	v_mov_b32_e32 v126, v0
	v_mov_b32_e32 v127, v0
	.p2align 6
	s_nop 0
	s_nop 0

;     __device__ bool next(int i, Unit& u) const { int pm, pn; if (!so.next(i, pm, pn)) return false; u.pm = pm; u.pn = pn; u.aoff = (unsigned)pm * BM * lda; u.boff = (unsigned)pn * BM * ldb; return true; }
;     __device__ __forceinline__ bool next(int i, Unit& u) const { int pm, pn; if (!so.next(i, pm, pn)) return false; u.pm = pm; u.pn = pn; u.aoff = (unsigned)pm * BM * lda; u.boff = (unsigned)(pm >> 4) * bstride + (unsigned)pn * BM * ldb; return true; }
;     __device__ __forceinline__ bool next(int i, Unit& u) const { int pm, pn; if (!so.next(i, pm, pn)) return false; u.pm = pm; u.pn = ((pn & 12) == 4 || (pn & 12) == 8) ? (pn ^ 12) : pn; u.aoff = (unsigned)pm * BM * lda; u.boff = (unsigned)pn * BM * ldb; return true; }
; template <class Epi, class Sched, bool ALIGN_EPI>
; __device__ __forceinline__ void gemm_phase(LAS unsigned char* lds, const Gemm g, const Sched& S, const Epi& E) {
;     ...
;         const bool has_next = S.next(ui + 1, nxt);
;         const char* nA = has_next ? (const char*)g.A + (size_t)nxt.aoff * 2 : cA; const char* nB = has_next ? (const char*)g.Bt + (size_t)nxt.boff * 2 : cB;
;     ...
; #pragma unroll
;         for (int a = 0; a < 2; ++a)
; #pragma unroll
;             for (int b = 0; b < 2; ++b)
; #pragma unroll
;                 for (int m = 0; m < 4; ++m)
; #pragma unroll
;                     for (int n = 0; n < 2; ++n) acc[a][b][m][n] = (f32x4){0.f, 0.f, 0.f, 0.f};
.LBB0_1147:
	s_lshl_b64 s[18:19], s[22:23], 1
	s_add_u32 s42, s50, s18
	s_addc_u32 s43, s51, s19
	s_and_b64 s[18:19], s[2:3], exec
	s_mov_b32 s41, s23
	s_cselect_b32 s74, s43, s5
	s_cselect_b32 s75, s42, s4
	s_lshl_b64 s[18:19], s[40:41], 1
	s_add_u32 s52, s8, s18
	s_addc_u32 s53, s9, s19
	s_and_b64 s[18:19], s[2:3], exec
	s_cselect_b32 s41, s53, s7
	s_cselect_b32 s76, s52, s6
	s_add_u32 s4, s4, 0x80080
	s_addc_u32 s5, s5, 0
	s_add_u32 s44, s6, 0x100
	v_mov_b32_e32 v0, 0
	s_addc_u32 s45, s7, 0
	s_mov_b32 s46, -2
	v_mov_b32_e32 v1, v0
	v_mov_b32_e32 v2, v0
	v_mov_b32_e32 v3, v0
	v_mov_b32_e32 v8, v0
	v_mov_b32_e32 v9, v0
	v_mov_b32_e32 v10, v0
	v_mov_b32_e32 v11, v0
	v_mov_b32_e32 v16, v0
	v_mov_b32_e32 v17, v0
	v_mov_b32_e32 v18, v0
	v_mov_b32_e32 v19, v0
	v_mov_b32_e32 v24, v0
	v_mov_b32_e32 v25, v0
	v_mov_b32_e32 v26, v0
	v_mov_b32_e32 v27, v0
	v_mov_b32_e32 v32, v0
	v_mov_b32_e32 v33, v0
	v_mov_b32_e32 v34, v0
	v_mov_b32_e32 v35, v0
	v_mov_b32_e32 v40, v0
	v_mov_b32_e32 v41, v0
	v_mov_b32_e32 v42, v0
	v_mov_b32_e32 v43, v0
	v_mov_b32_e32 v48, v0
	v_mov_b32_e32 v49, v0
	v_mov_b32_e32 v50, v0
	v_mov_b32_e32 v51, v0
	v_mov_b32_e32 v56, v0
	v_mov_b32_e32 v57, v0
	v_mov_b32_e32 v58, v0
	v_mov_b32_e32 v59, v0
	v_mov_b32_e32 v4, v0
	v_mov_b32_e32 v5, v0
	v_mov_b32_e32 v6, v0
	v_mov_b32_e32 v7, v0
	v_mov_b32_e32 v12, v0
	v_mov_b32_e32 v13, v0
	v_mov_b32_e32 v14, v0
	v_mov_b32_e32 v15, v0
	v_mov_b32_e32 v20, v0
	v_mov_b32_e32 v21, v0
	v_mov_b32_e32 v22, v0
	v_mov_b32_e32 v23, v0
	v_mov_b32_e32 v28, v0
	v_mov_b32_e32 v29, v0
	v_mov_b32_e32 v30, v0
	v_mov_b32_e32 v31, v0
	v_mov_b32_e32 v36, v0
	v_mov_b32_e32 v37, v0
	v_mov_b32_e32 v38, v0
	v_mov_b32_e32 v39, v0
	v_mov_b32_e32 v44, v0
	v_mov_b32_e32 v45, v0
	v_mov_b32_e32 v46, v0
	v_mov_b32_e32 v47, v0
	v_mov_b32_e32 v52, v0
	v_mov_b32_e32 v53, v0
	v_mov_b32_e32 v54, v0
	v_mov_b32_e32 v55, v0
	v_mov_b32_e32 v60, v0
	v_mov_b32_e32 v61, v0
	v_mov_b32_e32 v62, v0
	v_mov_b32_e32 v63, v0
	v_mov_b32_e32 v64, v0
	v_mov_b32_e32 v65, v0
	v_mov_b32_e32 v66, v0
	v_mov_b32_e32 v67, v0
	v_mov_b32_e32 v72, v0
	v_mov_b32_e32 v73, v0
	v_mov_b32_e32 v74, v0
	v_mov_b32_e32 v75, v0
	v_mov_b32_e32 v80, v0
	v_mov_b32_e32 v81, v0
	v_mov_b32_e32 v82, v0
	v_mov_b32_e32 v83, v0
	v_mov_b32_e32 v88, v0
	v_mov_b32_e32 v89, v0
	v_mov_b32_e32 v90, v0
	v_mov_b32_e32 v91, v0
	v_mov_b32_e32 v96, v0
	v_mov_b32_e32 v97, v0
	v_mov_b32_e32 v98, v0
	v_mov_b32_e32 v99, v0
	v_mov_b32_e32 v104, v0
	v_mov_b32_e32 v105, v0
	v_mov_b32_e32 v106, v0
	v_mov_b32_e32 v107, v0
	v_mov_b32_e32 v112, v0
	v_mov_b32_e32 v113, v0
	v_mov_b32_e32 v114, v0
	v_mov_b32_e32 v115, v0
	v_mov_b32_e32 v120, v0
	v_mov_b32_e32 v121, v0
	v_mov_b32_e32 v122, v0
	v_mov_b32_e32 v123, v0
	v_mov_b32_e32 v68, v0
	v_mov_b32_e32 v69, v0
	v_mov_b32_e32 v70, v0
	v_mov_b32_e32 v71, v0
	v_mov_b32_e32 v76, v0
	v_mov_b32_e32 v77, v0
	v_mov_b32_e32 v78, v0
	v_mov_b32_e32 v79, v0
	v_mov_b32_e32 v84, v0
	v_mov_b32_e32 v85, v0
	v_mov_b32_e32 v86, v0
	v_mov_b32_e32 v87, v0
	v_mov_b32_e32 v92, v0
	v_mov_b32_e32 v93, v0
	v_mov_b32_e32 v94, v0
	v_mov_b32_e32 v95, v0
	v_mov_b32_e32 v100, v0
	v_mov_b32_e32 v101, v0
	v_mov_b32_e32 v102, v0
	v_mov_b32_e32 v103, v0
	v_mov_b32_e32 v108, v0
	v_mov_b32_e32 v109, v0
	v_mov_b32_e32 v110, v0
	v_mov_b32_e32 v111, v0
	v_mov_b32_e32 v116, v0
	v_mov_b32_e32 v117, v0
	v_mov_b32_e32 v118, v0
	v_mov_b32_e32 v119, v0
	v_mov_b32_e32 v124, v0
	v_mov_b32_e32 v125, v0
	v_mov_b32_e32 v126, v0
	v_mov_b32_e32 v127, v0
	.p2align 6
	s_nop 0
	s_nop 0

;     __device__ bool next(int i, Unit& u) const { int pm, pn; if (!so.next(i, pm, pn)) return false; u.pm = pm; u.pn = pn; u.aoff = (unsigned)pm * BM * lda; u.boff = (unsigned)pn * BM * ldb; return true; }
;     __device__ __forceinline__ bool next(int i, Unit& u) const { int pm, pn; if (!so.next(i, pm, pn)) return false; u.pm = pm; u.pn = pn; u.aoff = (unsigned)pm * BM * lda; u.boff = (unsigned)(pm >> 4) * bstride + (unsigned)pn * BM * ldb; return true; }
;     __device__ __forceinline__ bool next(int i, Unit& u) const { int pm, pn; if (!so.next(i, pm, pn)) return false; u.pm = pm; u.pn = ((pn & 12) == 4 || (pn & 12) == 8) ? (pn ^ 12) : pn; u.aoff = (unsigned)pm * BM * lda; u.boff = (unsigned)pn * BM * ldb; return true; }
; template <class Epi, class Sched, bool ALIGN_EPI>
; __device__ __forceinline__ void gemm_phase(LAS unsigned char* lds, const Gemm g, const Sched& S, const Epi& E) {
;     ...
;         const bool has_next = S.next(ui + 1, nxt);
;         const char* nA = has_next ? (const char*)g.A + (size_t)nxt.aoff * 2 : cA; const char* nB = has_next ? (const char*)g.Bt + (size_t)nxt.boff * 2 : cB;
;     ...
; #pragma unroll
;         for (int a = 0; a < 2; ++a)
; #pragma unroll
;             for (int b = 0; b < 2; ++b)
; #pragma unroll
;                 for (int m = 0; m < 4; ++m)
; #pragma unroll
;                     for (int n = 0; n < 2; ++n) acc[a][b][m][n] = (f32x4){0.f, 0.f, 0.f, 0.f};
.LBB0_1233:
	s_lshl_b64 s[18:19], s[6:7], 1
	s_add_u32 s30, s28, s18
	s_addc_u32 s31, s29, s19
	s_and_b64 s[18:19], s[4:5], exec
	s_mov_b32 s27, s7
	s_cselect_b32 s70, s31, s39
	s_cselect_b32 s71, s30, s38
	s_lshl_b64 s[18:19], s[26:27], 1
	s_add_u32 s36, s82, s18
	s_addc_u32 s37, s83, s19
	s_and_b64 s[18:19], s[4:5], exec
	s_cselect_b32 s27, s37, s41
	s_cselect_b32 s72, s36, s40
	s_add_u32 s38, s38, 0x160080
	s_addc_u32 s39, s39, 0
	s_add_u32 s44, s40, 0x100
	v_mov_b32_e32 v0, 0
	s_addc_u32 s45, s41, 0
	s_mov_b32 s46, -2
	s_waitcnt lgkmcnt(0)
	v_mov_b32_e32 v1, v0
	v_mov_b32_e32 v2, v0
	v_mov_b32_e32 v3, v0
	v_mov_b32_e32 v4, v0
	v_mov_b32_e32 v5, v0
	v_mov_b32_e32 v6, v0
	v_mov_b32_e32 v7, v0
	v_mov_b32_e32 v16, v0
	v_mov_b32_e32 v17, v0
	v_mov_b32_e32 v18, v0
	v_mov_b32_e32 v19, v0
	v_mov_b32_e32 v20, v0
	v_mov_b32_e32 v21, v0
	v_mov_b32_e32 v22, v0
	v_mov_b32_e32 v23, v0
	v_mov_b32_e32 v32, v0
	v_mov_b32_e32 v33, v0
	v_mov_b32_e32 v34, v0
	v_mov_b32_e32 v35, v0
	v_mov_b32_e32 v36, v0
	v_mov_b32_e32 v37, v0
	v_mov_b32_e32 v38, v0
	v_mov_b32_e32 v39, v0
	v_mov_b32_e32 v48, v0
	v_mov_b32_e32 v49, v0
	v_mov_b32_e32 v50, v0
	v_mov_b32_e32 v51, v0
	v_mov_b32_e32 v52, v0
	v_mov_b32_e32 v53, v0
	v_mov_b32_e32 v54, v0
	v_mov_b32_e32 v55, v0
	v_mov_b32_e32 v8, v0
	v_mov_b32_e32 v9, v0
	v_mov_b32_e32 v10, v0
	v_mov_b32_e32 v11, v0
	v_mov_b32_e32 v12, v0
	v_mov_b32_e32 v13, v0
	v_mov_b32_e32 v14, v0
	v_mov_b32_e32 v15, v0
	v_mov_b32_e32 v24, v0
	v_mov_b32_e32 v25, v0
	v_mov_b32_e32 v26, v0
	v_mov_b32_e32 v27, v0
	v_mov_b32_e32 v28, v0
	v_mov_b32_e32 v29, v0
	v_mov_b32_e32 v30, v0
	v_mov_b32_e32 v31, v0
	v_mov_b32_e32 v40, v0
	v_mov_b32_e32 v41, v0
	v_mov_b32_e32 v42, v0
	v_mov_b32_e32 v43, v0
	v_mov_b32_e32 v44, v0
	v_mov_b32_e32 v45, v0
	v_mov_b32_e32 v46, v0
	v_mov_b32_e32 v47, v0
	v_mov_b32_e32 v56, v0
	v_mov_b32_e32 v57, v0
	v_mov_b32_e32 v58, v0
	v_mov_b32_e32 v59, v0
	v_mov_b32_e32 v60, v0
	v_mov_b32_e32 v61, v0
	v_mov_b32_e32 v62, v0
	v_mov_b32_e32 v63, v0
	v_mov_b32_e32 v64, v0
	v_mov_b32_e32 v65, v0
	v_mov_b32_e32 v66, v0
	v_mov_b32_e32 v67, v0
	v_mov_b32_e32 v68, v0
	v_mov_b32_e32 v69, v0
	v_mov_b32_e32 v70, v0
	v_mov_b32_e32 v71, v0
	v_mov_b32_e32 v80, v0
	v_mov_b32_e32 v81, v0
	v_mov_b32_e32 v82, v0
	v_mov_b32_e32 v83, v0
	v_mov_b32_e32 v84, v0
	v_mov_b32_e32 v85, v0
	v_mov_b32_e32 v86, v0
	v_mov_b32_e32 v87, v0
	v_mov_b32_e32 v96, v0
	v_mov_b32_e32 v97, v0
	v_mov_b32_e32 v98, v0
	v_mov_b32_e32 v99, v0
	v_mov_b32_e32 v100, v0
	v_mov_b32_e32 v101, v0
	v_mov_b32_e32 v102, v0
	v_mov_b32_e32 v103, v0
	v_mov_b32_e32 v112, v0
	v_mov_b32_e32 v113, v0
	v_mov_b32_e32 v114, v0
	v_mov_b32_e32 v115, v0
	v_mov_b32_e32 v116, v0
	v_mov_b32_e32 v117, v0
	v_mov_b32_e32 v118, v0
	v_mov_b32_e32 v119, v0
	v_mov_b32_e32 v72, v0
	v_mov_b32_e32 v73, v0
	v_mov_b32_e32 v74, v0
	v_mov_b32_e32 v75, v0
	v_mov_b32_e32 v76, v0
	v_mov_b32_e32 v77, v0
	v_mov_b32_e32 v78, v0
	v_mov_b32_e32 v79, v0
	v_mov_b32_e32 v88, v0
	v_mov_b32_e32 v89, v0
	v_mov_b32_e32 v90, v0
	v_mov_b32_e32 v91, v0
	v_mov_b32_e32 v92, v0
	v_mov_b32_e32 v93, v0
	v_mov_b32_e32 v94, v0
	v_mov_b32_e32 v95, v0
	v_mov_b32_e32 v104, v0
	v_mov_b32_e32 v105, v0
	v_mov_b32_e32 v106, v0
	v_mov_b32_e32 v107, v0
	v_mov_b32_e32 v108, v0
	v_mov_b32_e32 v109, v0
	v_mov_b32_e32 v110, v0
	v_mov_b32_e32 v111, v0
	v_mov_b32_e32 v120, v0
	v_mov_b32_e32 v121, v0
	v_mov_b32_e32 v122, v0
	v_mov_b32_e32 v123, v0
	v_mov_b32_e32 v124, v0
	v_mov_b32_e32 v125, v0
	v_mov_b32_e32 v126, v0
	v_mov_b32_e32 v127, v0
	.p2align 6
	s_nop 0
	s_nop 0

;     __device__ bool next(int i, Unit& u) const { int pm, pn; if (!so.next(i, pm, pn)) return false; u.pm = pm; u.pn = pn; u.aoff = (unsigned)pm * BM * lda; u.boff = (unsigned)pn * BM * ldb; return true; }
;     __device__ __forceinline__ bool next(int i, Unit& u) const { int pm, pn; if (!so.next(i, pm, pn)) return false; u.pm = pm; u.pn = pn; u.aoff = (unsigned)pm * BM * lda; u.boff = (unsigned)(pm >> 4) * bstride + (unsigned)pn * BM * ldb; return true; }
;     __device__ __forceinline__ bool next(int i, Unit& u) const { int pm, pn; if (!so.next(i, pm, pn)) return false; u.pm = pm; u.pn = ((pn & 12) == 4 || (pn & 12) == 8) ? (pn ^ 12) : pn; u.aoff = (unsigned)pm * BM * lda; u.boff = (unsigned)pn * BM * ldb; return true; }
; template <class Epi, class Sched, bool ALIGN_EPI>
; __device__ __forceinline__ void gemm_phase(LAS unsigned char* lds, const Gemm g, const Sched& S, const Epi& E) {
;     ...
;         const bool has_next = S.next(ui + 1, nxt);
;         const char* nA = has_next ? (const char*)g.A + (size_t)nxt.aoff * 2 : cA; const char* nB = has_next ? (const char*)g.Bt + (size_t)nxt.boff * 2 : cB;
;     ...
; #pragma unroll
;         for (int a = 0; a < 2; ++a)
; #pragma unroll
;             for (int b = 0; b < 2; ++b)
; #pragma unroll
;                 for (int m = 0; m < 4; ++m)
; #pragma unroll
;                     for (int n = 0; n < 2; ++n) acc[a][b][m][n] = (f32x4){0.f, 0.f, 0.f, 0.f};
.LBB0_1277:
	s_mov_b32 s39, s25
	s_lshl_b64 s[18:19], s[38:39], 1
	s_add_u32 s42, s28, s18
	s_addc_u32 s43, s29, s19
	s_and_b64 s[18:19], s[8:9], exec
	s_mov_b32 s41, s25
	s_cselect_b32 s11, s43, s55
	s_cselect_b32 s39, s42, s54
	s_lshl_b64 s[18:19], s[40:41], 1
	s_add_u32 s52, s82, s18
	s_addc_u32 s53, s83, s19
	s_and_b64 s[18:19], s[8:9], exec
	s_cselect_b32 s41, s53, s57
	s_cselect_b32 s78, s52, s56
	s_add_u32 s54, s54, 0x160080
	s_addc_u32 s55, s55, 0
	s_add_u32 s44, s56, 0x100
	v_mov_b32_e32 v0, 0
	s_addc_u32 s45, s57, 0
	s_mov_b32 s46, -2
	v_mov_b32_e32 v1, v0
	v_mov_b32_e32 v2, v0
	v_mov_b32_e32 v3, v0
	v_mov_b32_e32 v4, v0
	v_mov_b32_e32 v5, v0
	v_mov_b32_e32 v6, v0
	v_mov_b32_e32 v7, v0
	v_mov_b32_e32 v16, v0
	v_mov_b32_e32 v17, v0
	v_mov_b32_e32 v18, v0
	v_mov_b32_e32 v19, v0
	v_mov_b32_e32 v20, v0
	v_mov_b32_e32 v21, v0
	v_mov_b32_e32 v22, v0
	v_mov_b32_e32 v23, v0
	v_mov_b32_e32 v32, v0
	v_mov_b32_e32 v33, v0
	v_mov_b32_e32 v34, v0
	v_mov_b32_e32 v35, v0
	v_mov_b32_e32 v36, v0
	v_mov_b32_e32 v37, v0
	v_mov_b32_e32 v38, v0
	v_mov_b32_e32 v39, v0
	v_mov_b32_e32 v48, v0
	v_mov_b32_e32 v49, v0
	v_mov_b32_e32 v50, v0
	v_mov_b32_e32 v51, v0
	v_mov_b32_e32 v52, v0
	v_mov_b32_e32 v53, v0
	v_mov_b32_e32 v54, v0
	v_mov_b32_e32 v55, v0
	v_mov_b32_e32 v8, v0
	v_mov_b32_e32 v9, v0
	v_mov_b32_e32 v10, v0
	v_mov_b32_e32 v11, v0
	v_mov_b32_e32 v12, v0
	v_mov_b32_e32 v13, v0
	v_mov_b32_e32 v14, v0
	v_mov_b32_e32 v15, v0
	v_mov_b32_e32 v24, v0
	v_mov_b32_e32 v25, v0
	v_mov_b32_e32 v26, v0
	v_mov_b32_e32 v27, v0
	v_mov_b32_e32 v28, v0
	v_mov_b32_e32 v29, v0
	v_mov_b32_e32 v30, v0
	v_mov_b32_e32 v31, v0
	v_mov_b32_e32 v40, v0
	v_mov_b32_e32 v41, v0
	v_mov_b32_e32 v42, v0
	v_mov_b32_e32 v43, v0
	v_mov_b32_e32 v44, v0
	v_mov_b32_e32 v45, v0
	v_mov_b32_e32 v46, v0
	v_mov_b32_e32 v47, v0
	v_mov_b32_e32 v56, v0
	v_mov_b32_e32 v57, v0
	v_mov_b32_e32 v58, v0
	v_mov_b32_e32 v59, v0
	v_mov_b32_e32 v60, v0
	v_mov_b32_e32 v61, v0
	v_mov_b32_e32 v62, v0
	v_mov_b32_e32 v63, v0
	v_mov_b32_e32 v64, v0
	v_mov_b32_e32 v65, v0
	v_mov_b32_e32 v66, v0
	v_mov_b32_e32 v67, v0
	v_mov_b32_e32 v68, v0
	v_mov_b32_e32 v69, v0
	v_mov_b32_e32 v70, v0
	v_mov_b32_e32 v71, v0
	v_mov_b32_e32 v80, v0
	v_mov_b32_e32 v81, v0
	v_mov_b32_e32 v82, v0
	v_mov_b32_e32 v83, v0
	v_mov_b32_e32 v84, v0
	v_mov_b32_e32 v85, v0
	v_mov_b32_e32 v86, v0
	v_mov_b32_e32 v87, v0
	v_mov_b32_e32 v96, v0
	v_mov_b32_e32 v97, v0
	v_mov_b32_e32 v98, v0
	v_mov_b32_e32 v99, v0
	v_mov_b32_e32 v100, v0
	v_mov_b32_e32 v101, v0
	v_mov_b32_e32 v102, v0
	v_mov_b32_e32 v103, v0
	v_mov_b32_e32 v112, v0
	v_mov_b32_e32 v113, v0
	v_mov_b32_e32 v114, v0
	v_mov_b32_e32 v115, v0
	v_mov_b32_e32 v116, v0
	v_mov_b32_e32 v117, v0
	v_mov_b32_e32 v118, v0
	v_mov_b32_e32 v119, v0
	v_mov_b32_e32 v72, v0
	v_mov_b32_e32 v73, v0
	v_mov_b32_e32 v74, v0
	v_mov_b32_e32 v75, v0
	v_mov_b32_e32 v76, v0
	v_mov_b32_e32 v77, v0
	v_mov_b32_e32 v78, v0
	v_mov_b32_e32 v79, v0
	v_mov_b32_e32 v88, v0
	v_mov_b32_e32 v89, v0
	v_mov_b32_e32 v90, v0
	v_mov_b32_e32 v91, v0
	v_mov_b32_e32 v92, v0
	v_mov_b32_e32 v93, v0
	v_mov_b32_e32 v94, v0
	v_mov_b32_e32 v95, v0
	v_mov_b32_e32 v104, v0
	v_mov_b32_e32 v105, v0
	v_mov_b32_e32 v106, v0
	v_mov_b32_e32 v107, v0
	v_mov_b32_e32 v108, v0
	v_mov_b32_e32 v109, v0
	v_mov_b32_e32 v110, v0
	v_mov_b32_e32 v111, v0
	v_mov_b32_e32 v120, v0
	v_mov_b32_e32 v121, v0
	v_mov_b32_e32 v122, v0
	v_mov_b32_e32 v123, v0
	v_mov_b32_e32 v124, v0
	v_mov_b32_e32 v125, v0
	v_mov_b32_e32 v126, v0
	v_mov_b32_e32 v127, v0
	.p2align 6
	s_nop 0
	s_nop 0
